# W1 transposes + shift-table (cb) items of FFN instance 3 moved from prologue/phase2 to idle CUs in FFN2-up and FFN3-up tail rounds
# speedup vs baseline: 1.0477x; 1.0008x over previous
; __device__ __forceinline__ void prologue(const Params& p, LAS unsigned char* lds) {
;     ...
;         for (int it = gw; it < NITEMS; it += NGW) {
;             int r = it;
;             if (r < 4 * I_W1) { const int mi = r / I_W1; r -= mi * I_W1; const int kb = r / 176, nb = r % 176;
;                 transpose_item(p.in[I_FFNWIN] + (size_t)mi * D * NFF1, D, NFF1, (bf16_t*)(ws + WS_W1T + mi * SZ_W1T), paired_src(nb * 32, DFF), nb * 32, kb * 64, scr, lane); continue; }
.LBB0_28:
	v_mov_b32_e32 v254, 0x23f00
	v_mov_b32_e32 v255, s30
	ds_write_b32 v254, v255
	v_mov_b32_e32 v255, s31
	ds_write_b32 v254, v255 offset:4
	v_lshl_add_u32 v181, s84, 3, v218
	s_movk_i32 s0, 0x4b00
	s_lshl_b32 s94, s82, 3
	v_cmp_gt_i32_e32 vcc, s0, v181
	v_lshlrev_b32_e32 v3, 3, v176
	s_barrier
	s_and_saveexec_b64 s[0:1], vcc
	s_cbranch_execz .LBB0_49
	v_lshrrev_b32_e32 v17, 5, v178
	v_lshl_add_u32 v6, v218, 14, 0
	v_lshlrev_b32_e32 v14, 2, v16
	v_mul_u32_u24_e32 v0, 0x84, v17
	v_and_b32_e32 v2, 56, v3
	v_mov_b32_e32 v1, 0
	v_add3_u32 v22, v6, v14, v0
	v_lshlrev_b32_e32 v0, 1, v2
	v_lshrrev_b32_e32 v23, 3, v178
	v_lshl_add_u64 v[8:9], s[80:81], 0, v[0:1]
	s_mov_b64 s[2:3], 0x4b00000
	v_mul_u32_u24_e32 v7, 0x84, v2
	v_lshl_add_u64 v[4:5], v[8:9], 0, s[2:3]
	v_lshlrev_b32_e32 v0, 2, v23
	s_mov_b64 s[2:3], 0x4900000
	v_add3_u32 v24, v6, v7, v0
	v_lshl_add_u64 v[6:7], v[8:9], 0, s[2:3]
	s_mov_b64 s[2:3], 0x4400000
	v_lshl_add_u64 v[8:9], v[8:9], 0, s[2:3]
	s_add_u32 s2, s80, 0x2e00000
	s_addc_u32 s3, s81, 0
	v_readlane_b32 s36, v253, 0
	v_lshlrev_b32_e32 v0, 5, v218
	s_add_u32 s4, s80, 0x200000
	v_mov_b32_e32 v15, v1
	v_readlane_b32 s37, v253, 1
	v_readlane_b32 s38, v253, 2
	v_readlane_b32 s39, v253, 3
	v_readlane_b32 s40, v253, 4
	v_readlane_b32 s50, v253, 14
	v_readlane_b32 s51, v253, 15
	v_lshl_add_u32 v28, s84, 8, v0
	v_lshlrev_b32_e32 v0, 1, v218
	v_or_b32_e32 v25, 8, v23
	v_or_b32_e32 v26, 16, v23
	v_or_b32_e32 v27, 24, v23
	s_addc_u32 s5, s81, 0
	v_lshl_add_u64 v[10:11], s[72:73], 0, v[14:15]
	v_lshl_add_u64 v[12:13], s[50:51], 0, v[14:15]
	v_lshl_add_u64 v[14:15], s[38:39], 0, v[14:15]
	s_lshl_b32 s18, s82, 8
	v_lshl_add_u32 v29, s84, 4, v0
	s_lshl_b32 s19, s82, 4
	s_mov_b64 s[6:7], 0
	s_movk_i32 s22, 0x2bff
	s_movk_i32 s23, 0x41ff
	s_movk_i32 s24, 0x46ff
	s_movk_i32 s25, 0x48ff
	s_movk_i32 s26, 0x80
	s_movk_i32 s27, 0x180
	s_mov_b32 s33, 0xb00000
	s_mov_b32 s34, 0x580000
	s_mov_b32 s35, 0x2e8ba2e9
	s_movk_i32 s36, 0xb0
	s_mov_b32 s37, 0x1600000
	s_movk_i32 s38, 0xa80
	s_movk_i32 s39, 0x5800
	s_movk_i32 s40, 0x4aff
	v_add_u32_e32 v30, 0x400, v22
	v_add_u32_e32 v31, 0x800, v22
	v_add_u32_e32 v32, 0xc00, v22
	v_add_u32_e32 v33, 0x1000, v22
	v_add_u32_e32 v34, 0x1400, v22
	v_add_u32_e32 v35, 0x1800, v22
	v_add_u32_e32 v36, 0x1c00, v22
	v_mov_b32_e32 v37, 5
	v_mov_b32_e32 v38, 6
	v_mov_b32_e32 v39, v181
	v_readlane_b32 s41, v253, 5
	v_readlane_b32 s42, v253, 6
	v_readlane_b32 s43, v253, 7
	v_readlane_b32 s44, v253, 8
	v_readlane_b32 s45, v253, 9
	v_readlane_b32 s46, v253, 10
	v_readlane_b32 s47, v253, 11
	v_readlane_b32 s48, v253, 12
	v_readlane_b32 s49, v253, 13
	s_branch .LBB0_31
.LBB0_30:
	s_or_b64 exec, exec, s[8:9]
	v_add_u32_e32 v39, s94, v39
	v_add_u32_e32 v28, s18, v28
	v_add_u32_e32 v29, s19, v29
	v_mov_b32_e32 v255, 0x20ff
	v_cmp_lt_u32_e32 vcc, v255, v39
	v_mov_b32_e32 v255, 0x2c00
	v_cmp_gt_u32_e64 s[98:99], v255, v39
	s_and_b64 vcc, vcc, s[98:99]
	s_cmpk_eq_u32 s82, 0x100
	s_cselect_b64 s[98:99], -1, 0
	s_and_b64 vcc, vcc, s[98:99]
	v_cndmask_b32_e64 v255, 0, 1, vcc
	v_mul_u32_u24_e32 v254, 0xb00, v255
	v_add_u32_e32 v39, v39, v254
	v_mul_u32_u24_e32 v254, 0x16000, v255
	v_add_u32_e32 v28, v28, v254
	v_mul_u32_u24_e32 v254, 0x1600, v255
	v_add_u32_e32 v29, v29, v254
	v_mov_b32_e32 v255, 0x317f
	v_cmp_lt_u32_e32 vcc, v255, v39
	v_mov_b32_e32 v255, 0x4200
	v_cmp_gt_u32_e64 s[98:99], v255, v39
	s_and_b64 vcc, vcc, s[98:99]
	s_cmpk_eq_u32 s82, 0x100
	s_cselect_b64 s[98:99], -1, 0
	s_and_b64 vcc, vcc, s[98:99]
	v_cndmask_b32_e64 v255, 0, 1, vcc
	v_mul_u32_u24_e32 v254, 0x1080, v255
	v_add_u32_e32 v39, v39, v254
	v_mul_u32_u24_e32 v254, 0x21000, v255
	v_add_u32_e32 v28, v28, v254
	v_mul_u32_u24_e32 v254, 0x2100, v255
	v_add_u32_e32 v29, v29, v254
	v_cmp_lt_i32_e32 vcc, s40, v39
	s_or_b64 s[6:7], vcc, s[6:7]
	s_andn2_b64 exec, exec, s[6:7]
	s_cbranch_execz .LBB0_49

; __device__ __forceinline__ void cb_tables(const Params& p) {
;     ...
;     for (int it = blockIdx.x + G * wave; it < 4 * 88 + 40 + 32; it += 8 * G) {
;         if (it < 352) { const int mi = it / 88, ch = it % 88, layer = mi >> 1, sub = mi & 1;
;             cb_item((const bf16_t*)(ws + WS_W1T + mi * SZ_W1T), D, D, ch * 64, MOD + (size_t)layer * 5 * 9216 + (sub ? 6 : 0) * 1024, (float*)(ws + WS_CB) + (size_t)mi * 5 * NFF1, NFF1, lane); }
.LBB0_151:
	s_cmpk_lg_u32 s82, 0x100
	s_cbranch_scc1 .Lcb_noskip
	v_readfirstlane_b32 s98, v193
	s_cmpk_lt_u32 s98, 0x108
	s_cbranch_scc1 .Lcb_noskip
	s_cmpk_ge_u32 s98, 0x160
	s_cbranch_scc1 .Lcb_noskip
	s_mov_b64 s[46:47], exec
	s_branch .LBB0_150

; #define LAS __attribute__((address_space(3)))
; __device__ __forceinline__ unsigned cvt_pk_bf16(float lo, float hi) { unsigned r; asm volatile("v_cvt_pk_bf16_f32 %0, %1, %2" : "=v"(r) : "v"(lo), "v"(hi)); return r; }
; #define ST16(grp, p, v) do { if ((NTG >> (grp)) & 1) NT16(p, v); else PL16(p, v); } while (0)
; __device__ __forceinline__ void transpose_item(const float* W, int K, int N, bf16_t* WT, int n0src, int n0dst, int k0, LAS float* scr, int lane) {
;     float v[32];
; #pragma unroll
;     for (int i = 0; i < 32; ++i) { const int kk = 2 * i + (lane >> 5); v[i] = W[(size_t)(k0 + kk) * N + n0src + (lane & 31)]; }
; #pragma unroll
;     for (int i = 0; i < 32; ++i) { const int kk = 2 * i + (lane >> 5); scr[kk * 33 + (lane & 31)] = v[i]; }
;     asm volatile("s_waitcnt lgkmcnt(0)" ::: "memory");
;     const int c = lane & 7;
; #pragma unroll
;     for (int j = 0; j < 4; ++j) { const int n = (lane >> 3) + 8 * j; const LAS float* s = scr + (8 * c) * 33 + n;
;         u32x4 o; o.x = cvt_pk_bf16(s[0 * 33], s[1 * 33]); o.y = cvt_pk_bf16(s[2 * 33], s[3 * 33]); o.z = cvt_pk_bf16(s[4 * 33], s[5 * 33]); o.w = cvt_pk_bf16(s[6 * 33], s[7 * 33]);
;         ST16(6, WT + (size_t)(n0dst + n) * K + k0 + 8 * c, o); }
;     asm volatile("s_waitcnt lgkmcnt(0)" ::: "memory");
; }
; __device__ __forceinline__ void prologue(const Params& p, LAS unsigned char* lds) {
;     ...
;             if (r < 4 * I_W2) { const int mi = r / I_W2; r -= mi * I_W2; const int kb = r / 32, nb = r % 32;
;                 transpose_item(p.in[I_FFNWOUT] + (size_t)mi * DFF * D, DFF, D, (bf16_t*)(ws + WS_W2T + mi * SZ_W2T), nb * 32, nb * 32, kb * 64, scr, lane); continue; }
.LBB0_976:
	s_waitcnt vmcnt(0)
	s_barrier
	s_cmpk_lg_u32 s78, 0x100
	s_cbranch_scc1 .Ltr_done_a
	s_cmpk_lt_u32 s68, 0x80
	s_cbranch_scc1 .Ltr_done_a
	s_mov_b64 s[38:39], exec
	s_mov_b64 exec, -1
	v_readfirstlane_b32 s99, v176
	s_lshr_b32 s99, s99, 6
	s_sub_i32 s37, s68, 0x80
	s_lshl_b32 s36, s37, 3
	s_add_i32 s36, s36, s99
	s_lshl_b32 s99, s99, 14
	v_and_b32_e32 v16, 63, v176
	v_and_b32_e32 v17, 31, v16
	v_lshrrev_b32_e32 v18, 5, v16
	v_mul_u32_u24_e32 v19, 0x84, v18
	v_lshl_add_u32 v19, v17, 2, v19
	v_add_u32_e32 v19, s99, v19
	v_and_b32_e32 v20, 7, v16
	v_lshrrev_b32_e32 v21, 3, v16
	v_mul_u32_u24_e32 v22, 0x420, v20
	v_lshl_add_u32 v22, v21, 2, v22
	v_add_u32_e32 v22, s99, v22
	v_lshlrev_b32_e32 v23, 12, v18
	v_lshl_add_u32 v23, v17, 2, v23
	v_mul_u32_u24_e32 v24, 0x1600, v21
	v_lshl_add_u32 v24, v20, 4, v24
	v_readlane_b32 s32, v253, 0
	v_readlane_b32 s33, v253, 1
	s_add_u32 s32, s32, 0xb00000
	s_addc_u32 s33, s33, 0
	s_add_u32 s34, s76, 0x3380000
	s_addc_u32 s35, s77, 0
	s_mov_b32 s98, s36
	s_cmpk_ge_u32 s98, 0x580
	s_cbranch_scc1 .Ltr_end_a0

; #define LAS __attribute__((address_space(3)))
; __device__ __forceinline__ unsigned cvt_pk_bf16(float lo, float hi) { unsigned r; asm volatile("v_cvt_pk_bf16_f32 %0, %1, %2" : "=v"(r) : "v"(lo), "v"(hi)); return r; }
; #define ST16(grp, p, v) do { if ((NTG >> (grp)) & 1) NT16(p, v); else PL16(p, v); } while (0)
; __device__ __forceinline__ void transpose_item(const float* W, int K, int N, bf16_t* WT, int n0src, int n0dst, int k0, LAS float* scr, int lane) {
;     float v[32];
; #pragma unroll
;     for (int i = 0; i < 32; ++i) { const int kk = 2 * i + (lane >> 5); v[i] = W[(size_t)(k0 + kk) * N + n0src + (lane & 31)]; }
; #pragma unroll
;     for (int i = 0; i < 32; ++i) { const int kk = 2 * i + (lane >> 5); scr[kk * 33 + (lane & 31)] = v[i]; }
;     asm volatile("s_waitcnt lgkmcnt(0)" ::: "memory");
;     const int c = lane & 7;
; #pragma unroll
;     for (int j = 0; j < 4; ++j) { const int n = (lane >> 3) + 8 * j; const LAS float* s = scr + (8 * c) * 33 + n;
;         u32x4 o; o.x = cvt_pk_bf16(s[0 * 33], s[1 * 33]); o.y = cvt_pk_bf16(s[2 * 33], s[3 * 33]); o.z = cvt_pk_bf16(s[4 * 33], s[5 * 33]); o.w = cvt_pk_bf16(s[6 * 33], s[7 * 33]);
;         ST16(6, WT + (size_t)(n0dst + n) * K + k0 + 8 * c, o); }
;     asm volatile("s_waitcnt lgkmcnt(0)" ::: "memory");
; }
; __device__ __forceinline__ void prologue(const Params& p, LAS unsigned char* lds) {
;     ...
;             if (r < 4 * I_W1) { const int mi = r / I_W1; r -= mi * I_W1; const int kb = r / 176, nb = r % 176;
;                 transpose_item(p.in[I_FFNWIN] + (size_t)mi * D * NFF1, D, NFF1, (bf16_t*)(ws + WS_W1T + mi * SZ_W1T), paired_src(nb * 32, DFF), nb * 32, kb * 64, scr, lane); continue; }
.Ltr_end_a0:
	v_mul_u32_u24_e32 v23, 0x5800, v18
	v_lshl_add_u32 v23, v17, 2, v23
	v_lshlrev_b32_e32 v24, 11, v21
	v_lshl_add_u32 v24, v20, 4, v24
	v_mov_b32_e32 v25, 0x23f00
	ds_read_b64 v[26:27], v25
	s_waitcnt lgkmcnt(0)
	v_readfirstlane_b32 s32, v26
	v_readfirstlane_b32 s33, v27
	s_add_u32 s32, s32, 0x4200000
	s_addc_u32 s33, s33, 0
	s_add_u32 s34, s76, 0x2300000
	s_addc_u32 s35, s77, 0
	s_mov_b32 s98, s36
	s_cmpk_ge_u32 s98, 0xb00
	s_cbranch_scc1 .Ltr_end_a1
.Ltr_loop_a1:
	s_and_b32 s100, s98, 15
	s_lshr_b32 s101, s98, 4
	s_lshr_b32 s0, s101, 3
	s_lshl_b32 s0, s0, 7
	s_and_b32 s1, s101, 7
	s_lshl_b32 s1, s1, 5
	s_add_u32 s0, s0, s1
	s_add_u32 s1, s0, 0xa80
	s_bitcmp1_b32 s101, 2
	s_cselect_b32 s0, s1, s0
	s_lshl_b32 s0, s0, 2
	s_mul_i32 s1, s100, 0x160000
	s_add_u32 s0, s0, s1
	s_add_u32 s0, s32, s0
	s_addc_u32 s1, s33, 0
	global_load_dword v32, v23, s[0:1] nt
	s_add_u32 s0, s0, 0xb000
	s_addc_u32 s1, s1, 0
	global_load_dword v33, v23, s[0:1] nt
	s_add_u32 s0, s0, 0xb000
	s_addc_u32 s1, s1, 0
	global_load_dword v34, v23, s[0:1] nt
	s_add_u32 s0, s0, 0xb000
	s_addc_u32 s1, s1, 0
	global_load_dword v35, v23, s[0:1] nt
	s_add_u32 s0, s0, 0xb000
	s_addc_u32 s1, s1, 0
	global_load_dword v36, v23, s[0:1] nt
	s_add_u32 s0, s0, 0xb000
	s_addc_u32 s1, s1, 0
	global_load_dword v37, v23, s[0:1] nt
	s_add_u32 s0, s0, 0xb000
	s_addc_u32 s1, s1, 0
	global_load_dword v38, v23, s[0:1] nt
	s_add_u32 s0, s0, 0xb000
	s_addc_u32 s1, s1, 0
	global_load_dword v39, v23, s[0:1] nt
	s_add_u32 s0, s0, 0xb000
	s_addc_u32 s1, s1, 0
	global_load_dword v40, v23, s[0:1] nt
	s_add_u32 s0, s0, 0xb000
	s_addc_u32 s1, s1, 0
	global_load_dword v41, v23, s[0:1] nt
	s_add_u32 s0, s0, 0xb000
	s_addc_u32 s1, s1, 0
	global_load_dword v42, v23, s[0:1] nt
	s_add_u32 s0, s0, 0xb000
	s_addc_u32 s1, s1, 0
	global_load_dword v43, v23, s[0:1] nt
	s_add_u32 s0, s0, 0xb000
	s_addc_u32 s1, s1, 0
	global_load_dword v44, v23, s[0:1] nt
	s_add_u32 s0, s0, 0xb000
	s_addc_u32 s1, s1, 0
	global_load_dword v45, v23, s[0:1] nt
	s_add_u32 s0, s0, 0xb000
	s_addc_u32 s1, s1, 0
	global_load_dword v46, v23, s[0:1] nt
	s_add_u32 s0, s0, 0xb000
	s_addc_u32 s1, s1, 0
	global_load_dword v47, v23, s[0:1] nt
	s_add_u32 s0, s0, 0xb000
	s_addc_u32 s1, s1, 0
	global_load_dword v48, v23, s[0:1] nt
	s_add_u32 s0, s0, 0xb000
	s_addc_u32 s1, s1, 0
	global_load_dword v49, v23, s[0:1] nt
	s_add_u32 s0, s0, 0xb000
	s_addc_u32 s1, s1, 0
	global_load_dword v50, v23, s[0:1] nt
	s_add_u32 s0, s0, 0xb000
	s_addc_u32 s1, s1, 0
	global_load_dword v51, v23, s[0:1] nt
	s_add_u32 s0, s0, 0xb000
	s_addc_u32 s1, s1, 0
	global_load_dword v52, v23, s[0:1] nt
	s_add_u32 s0, s0, 0xb000
	s_addc_u32 s1, s1, 0
	global_load_dword v53, v23, s[0:1] nt
	s_add_u32 s0, s0, 0xb000
	s_addc_u32 s1, s1, 0
	global_load_dword v54, v23, s[0:1] nt
	s_add_u32 s0, s0, 0xb000
	s_addc_u32 s1, s1, 0
	global_load_dword v55, v23, s[0:1] nt
	s_add_u32 s0, s0, 0xb000
	s_addc_u32 s1, s1, 0
	global_load_dword v56, v23, s[0:1] nt
	s_add_u32 s0, s0, 0xb000
	s_addc_u32 s1, s1, 0
	global_load_dword v57, v23, s[0:1] nt
	s_add_u32 s0, s0, 0xb000
	s_addc_u32 s1, s1, 0
	global_load_dword v58, v23, s[0:1] nt
	s_add_u32 s0, s0, 0xb000
	s_addc_u32 s1, s1, 0
	global_load_dword v59, v23, s[0:1] nt
	s_add_u32 s0, s0, 0xb000
	s_addc_u32 s1, s1, 0
	global_load_dword v60, v23, s[0:1] nt
	s_add_u32 s0, s0, 0xb000
	s_addc_u32 s1, s1, 0
	global_load_dword v61, v23, s[0:1] nt
	s_add_u32 s0, s0, 0xb000
	s_addc_u32 s1, s1, 0
	global_load_dword v62, v23, s[0:1] nt
	s_add_u32 s0, s0, 0xb000
	s_addc_u32 s1, s1, 0
	global_load_dword v63, v23, s[0:1] nt
	s_waitcnt vmcnt(31)
	ds_write_b32 v19, v32
	s_waitcnt vmcnt(30)
	ds_write_b32 v19, v33 offset:264
	s_waitcnt vmcnt(29)
	ds_write_b32 v19, v34 offset:528
	s_waitcnt vmcnt(28)
	ds_write_b32 v19, v35 offset:792
	s_waitcnt vmcnt(27)
; #define LAS __attribute__((address_space(3)))
; __device__ __forceinline__ unsigned cvt_pk_bf16(float lo, float hi) { unsigned r; asm volatile("v_cvt_pk_bf16_f32 %0, %1, %2" : "=v"(r) : "v"(lo), "v"(hi)); return r; }
; #define ST16(grp, p, v) do { if ((NTG >> (grp)) & 1) NT16(p, v); else PL16(p, v); } while (0)
; __device__ __forceinline__ void transpose_item(const float* W, int K, int N, bf16_t* WT, int n0src, int n0dst, int k0, LAS float* scr, int lane) {
;     ...
;     for (int i = 0; i < 32; ++i) { const int kk = 2 * i + (lane >> 5); scr[kk * 33 + (lane & 31)] = v[i]; }
;     asm volatile("s_waitcnt lgkmcnt(0)" ::: "memory");
;     const int c = lane & 7;
; #pragma unroll
;     for (int j = 0; j < 4; ++j) { const int n = (lane >> 3) + 8 * j; const LAS float* s = scr + (8 * c) * 33 + n;
;         u32x4 o; o.x = cvt_pk_bf16(s[0 * 33], s[1 * 33]); o.y = cvt_pk_bf16(s[2 * 33], s[3 * 33]); o.z = cvt_pk_bf16(s[4 * 33], s[5 * 33]); o.w = cvt_pk_bf16(s[6 * 33], s[7 * 33]);
;         ST16(6, WT + (size_t)(n0dst + n) * K + k0 + 8 * c, o); }
;     asm volatile("s_waitcnt lgkmcnt(0)" ::: "memory");
; }
	ds_write_b32 v19, v36 offset:1056
	s_waitcnt vmcnt(26)
	ds_write_b32 v19, v37 offset:1320
	s_waitcnt vmcnt(25)
	ds_write_b32 v19, v38 offset:1584
	s_waitcnt vmcnt(24)
	ds_write_b32 v19, v39 offset:1848
	s_waitcnt vmcnt(23)
	ds_write_b32 v19, v40 offset:2112
	s_waitcnt vmcnt(22)
	ds_write_b32 v19, v41 offset:2376
	s_waitcnt vmcnt(21)
	ds_write_b32 v19, v42 offset:2640
	s_waitcnt vmcnt(20)
	ds_write_b32 v19, v43 offset:2904
	s_waitcnt vmcnt(19)
	ds_write_b32 v19, v44 offset:3168
	s_waitcnt vmcnt(18)
	ds_write_b32 v19, v45 offset:3432
	s_waitcnt vmcnt(17)
	ds_write_b32 v19, v46 offset:3696
	s_waitcnt vmcnt(16)
	ds_write_b32 v19, v47 offset:3960
	s_waitcnt vmcnt(15)
	ds_write_b32 v19, v48 offset:4224
	s_waitcnt vmcnt(14)
	ds_write_b32 v19, v49 offset:4488
	s_waitcnt vmcnt(13)
	ds_write_b32 v19, v50 offset:4752
	s_waitcnt vmcnt(12)
	ds_write_b32 v19, v51 offset:5016
	s_waitcnt vmcnt(11)
	ds_write_b32 v19, v52 offset:5280
	s_waitcnt vmcnt(10)
	ds_write_b32 v19, v53 offset:5544
	s_waitcnt vmcnt(9)
	ds_write_b32 v19, v54 offset:5808
	s_waitcnt vmcnt(8)
	ds_write_b32 v19, v55 offset:6072
	s_waitcnt vmcnt(7)
	ds_write_b32 v19, v56 offset:6336
	s_waitcnt vmcnt(6)
	ds_write_b32 v19, v57 offset:6600
	s_waitcnt vmcnt(5)
	ds_write_b32 v19, v58 offset:6864
	s_waitcnt vmcnt(4)
	ds_write_b32 v19, v59 offset:7128
	s_waitcnt vmcnt(3)
	ds_write_b32 v19, v60 offset:7392
	s_waitcnt vmcnt(2)
	ds_write_b32 v19, v61 offset:7656
	s_waitcnt vmcnt(1)
	ds_write_b32 v19, v62 offset:7920
	s_waitcnt vmcnt(0)
	ds_write_b32 v19, v63 offset:8184
	s_lshl_b32 s0, s101, 16
	s_lshl_b32 s1, s100, 7
	s_add_u32 s0, s0, s1
	s_add_u32 s0, s34, s0
	s_addc_u32 s1, s35, 0
	s_waitcnt lgkmcnt(0)
	ds_read_b32 v64, v22
	ds_read_b32 v65, v22 offset:132
	ds_read_b32 v66, v22 offset:264
	ds_read_b32 v67, v22 offset:396
	ds_read_b32 v68, v22 offset:528
	ds_read_b32 v69, v22 offset:660
	ds_read_b32 v70, v22 offset:792
	ds_read_b32 v71, v22 offset:924
	ds_read_b32 v72, v22 offset:32
	ds_read_b32 v73, v22 offset:164
	ds_read_b32 v74, v22 offset:296
	ds_read_b32 v75, v22 offset:428
	ds_read_b32 v76, v22 offset:560
	ds_read_b32 v77, v22 offset:692
	ds_read_b32 v78, v22 offset:824
	ds_read_b32 v79, v22 offset:956
	ds_read_b32 v80, v22 offset:64
	ds_read_b32 v81, v22 offset:196
	ds_read_b32 v82, v22 offset:328
	ds_read_b32 v83, v22 offset:460
	ds_read_b32 v84, v22 offset:592
	ds_read_b32 v85, v22 offset:724
	ds_read_b32 v86, v22 offset:856
	ds_read_b32 v87, v22 offset:988
	ds_read_b32 v88, v22 offset:96
	ds_read_b32 v89, v22 offset:228
	ds_read_b32 v90, v22 offset:360
	ds_read_b32 v91, v22 offset:492
	ds_read_b32 v92, v22 offset:624
	ds_read_b32 v93, v22 offset:756
	ds_read_b32 v94, v22 offset:888
	ds_read_b32 v95, v22 offset:1020
	s_waitcnt lgkmcnt(15)
	v_cvt_pk_bf16_f32 v96, v64, v65
	v_cvt_pk_bf16_f32 v97, v66, v67
	v_cvt_pk_bf16_f32 v98, v68, v69
	v_cvt_pk_bf16_f32 v99, v70, v71
	global_store_dwordx4 v24, v[96:99], s[0:1]
	s_add_u32 s0, s0, 0x4000
	s_addc_u32 s1, s1, 0
	s_waitcnt lgkmcnt(15)
	v_cvt_pk_bf16_f32 v100, v72, v73
	v_cvt_pk_bf16_f32 v101, v74, v75
	v_cvt_pk_bf16_f32 v102, v76, v77
	v_cvt_pk_bf16_f32 v103, v78, v79
	global_store_dwordx4 v24, v[100:103], s[0:1]
	s_add_u32 s0, s0, 0x4000
	s_addc_u32 s1, s1, 0
	s_waitcnt lgkmcnt(8)
	v_cvt_pk_bf16_f32 v104, v80, v81
	v_cvt_pk_bf16_f32 v105, v82, v83
	v_cvt_pk_bf16_f32 v106, v84, v85
	v_cvt_pk_bf16_f32 v107, v86, v87
	global_store_dwordx4 v24, v[104:107], s[0:1]
	s_add_u32 s0, s0, 0x4000
	s_addc_u32 s1, s1, 0
	s_waitcnt lgkmcnt(0)
	v_cvt_pk_bf16_f32 v108, v88, v89
	v_cvt_pk_bf16_f32 v109, v90, v91
	v_cvt_pk_bf16_f32 v110, v92, v93
	v_cvt_pk_bf16_f32 v111, v94, v95
	global_store_dwordx4 v24, v[108:111], s[0:1]
	s_add_i32 s98, s98, 0x400
	s_cmpk_lt_u32 s98, 0xb00
	s_cbranch_scc1 .Ltr_loop_a1
.Ltr_end_a1:
.Ltr_fin_a:
	s_mov_b64 exec, s[38:39]

; __device__ __forceinline__ void cb_item(const bf16_t* WT, int ldw, int K, int n0, const float* shift, float* out, int ostride, int lane) {
;     const bf16_t* wp = WT + (size_t)(n0 + lane) * ldw;
;     float a[5] = {0.f, 0.f, 0.f, 0.f, 0.f};
; #pragma unroll 4
;     for (int k8 = 0; k8 < K; k8 += 8) {
;         const u32x4 q = *(const u32x4*)(wp + k8);
;         float w[8];
; #pragma unroll
;         for (int e = 0; e < 4; ++e) { w[2 * e] = __uint_as_float(q[e] << 16); w[2 * e + 1] = __uint_as_float(q[e] & 0xffff0000u); }
; #pragma unroll
;         for (int b = 0; b < 5; ++b) { const float* sp = shift + (size_t)b * 9216 + k8;
; #pragma unroll
;             for (int e = 0; e < 8; ++e) a[b] += w[e] * sp[e]; }
;     }
; #pragma unroll
;     for (int b = 0; b < 5; ++b) out[(size_t)b * ostride + n0 + lane] = a[b];
; }
.LBB0_1141:
	s_waitcnt vmcnt(0)
	s_barrier
	s_cmpk_lg_u32 s78, 0x100
	s_cbranch_scc1 .Ltr_done_b
	s_cmpk_lt_u32 s68, 0x80
	s_cbranch_scc1 .Ltr_done_b
	s_mov_b64 s[38:39], exec
	s_mov_b64 exec, -1
	v_readfirstlane_b32 s99, v176
	s_lshr_b32 s99, s99, 6
	s_sub_i32 s37, s68, 0x80
	s_cmp_lg_u32 s99, 0
	s_cbranch_scc1 .Ltr_w17_b
	s_cmpk_ge_u32 s37, 0x58
	s_cbranch_scc1 .Ltr_fin_b
	v_and_b32_e32 v16, 63, v176
	s_lshl_b32 s0, s37, 17
	s_add_u32 s0, s0, 0x2300000
	s_add_u32 s32, s76, s0
	s_addc_u32 s33, s77, 0
	s_add_u32 s34, s76, 0x33000
	s_addc_u32 s35, s77, 0
	v_lshlrev_b32_e32 v17, 11, v16
	v_mul_u32_u24_e32 v18, 0xa0, v16
	v_lshlrev_b32_e32 v19, 5, v16
	v_mov_b32_e32 v20, 0
	v_mov_b32_e32 v21, 0
	v_mov_b32_e32 v22, 0
	v_mov_b32_e32 v23, 0
	v_mov_b32_e32 v24, 0
	s_add_u32 s0, s34, 0x0
	s_addc_u32 s1, s35, 0
	global_load_dwordx4 v[28:31], v19, s[0:1]
	global_load_dwordx4 v[32:35], v19, s[0:1] offset:16
	s_add_u32 s0, s0, 0x9000
	s_addc_u32 s1, s1, 0
	global_load_dwordx4 v[36:39], v19, s[0:1]
	global_load_dwordx4 v[40:43], v19, s[0:1] offset:16
	s_add_u32 s0, s0, 0x9000
	s_addc_u32 s1, s1, 0
	global_load_dwordx4 v[44:47], v19, s[0:1]
	global_load_dwordx4 v[48:51], v19, s[0:1] offset:16
	s_add_u32 s0, s0, 0x9000
	s_addc_u32 s1, s1, 0
	global_load_dwordx4 v[52:55], v19, s[0:1]
	global_load_dwordx4 v[56:59], v19, s[0:1] offset:16
	s_add_u32 s0, s0, 0x9000
	s_addc_u32 s1, s1, 0
	global_load_dwordx4 v[140:143], v19, s[0:1]
	global_load_dwordx4 v[144:147], v19, s[0:1] offset:16
	s_waitcnt vmcnt(0)
	ds_write_b128 v18, v[28:31]
	ds_write_b128 v18, v[32:35] offset:16
	ds_write_b128 v18, v[36:39] offset:32
	ds_write_b128 v18, v[40:43] offset:48
	ds_write_b128 v18, v[44:47] offset:64
	ds_write_b128 v18, v[48:51] offset:80
	ds_write_b128 v18, v[52:55] offset:96
	ds_write_b128 v18, v[56:59] offset:112
	ds_write_b128 v18, v[140:143] offset:128
	ds_write_b128 v18, v[144:147] offset:144
	s_waitcnt lgkmcnt(0)
	v_add_u32_e32 v25, 0x0, v17
	v_mov_b32_e32 v26, 0
	global_load_dwordx4 v[28:31], v25, s[32:33]
	global_load_dwordx4 v[32:35], v25, s[32:33] offset:16
	global_load_dwordx4 v[36:39], v25, s[32:33] offset:32
	global_load_dwordx4 v[40:43], v25, s[32:33] offset:48
	global_load_dwordx4 v[44:47], v25, s[32:33] offset:64
	global_load_dwordx4 v[48:51], v25, s[32:33] offset:80
	global_load_dwordx4 v[52:55], v25, s[32:33] offset:96
	global_load_dwordx4 v[56:59], v25, s[32:33] offset:112
	ds_read_b128 v[60:63], v26
	ds_read_b128 v[64:67], v26 offset:16
	ds_read_b128 v[68:71], v26 offset:32
	ds_read_b128 v[72:75], v26 offset:48
	ds_read_b128 v[76:79], v26 offset:64
	ds_read_b128 v[80:83], v26 offset:80
	ds_read_b128 v[84:87], v26 offset:96
	ds_read_b128 v[88:91], v26 offset:112
	ds_read_b128 v[92:95], v26 offset:128
	ds_read_b128 v[96:99], v26 offset:144
	s_mov_b32 s100, 8
.Lcb_loop_b_0:
	ds_read_b128 v[100:103], v26 offset:160
	ds_read_b128 v[104:107], v26 offset:176
	ds_read_b128 v[108:111], v26 offset:192
	ds_read_b128 v[112:115], v26 offset:208
	ds_read_b128 v[116:119], v26 offset:224
	ds_read_b128 v[120:123], v26 offset:240
	ds_read_b128 v[124:127], v26 offset:256
	ds_read_b128 v[128:131], v26 offset:272
	ds_read_b128 v[132:135], v26 offset:288
	ds_read_b128 v[136:139], v26 offset:304
	s_waitcnt vmcnt(7)
	v_lshlrev_b32_e32 v148, 16, v28
	v_and_b32_e32 v149, 0xffff0000, v28
	v_lshlrev_b32_e32 v150, 16, v29
	v_and_b32_e32 v151, 0xffff0000, v29
	v_lshlrev_b32_e32 v152, 16, v30
	v_and_b32_e32 v153, 0xffff0000, v30
	v_lshlrev_b32_e32 v154, 16, v31
	v_and_b32_e32 v155, 0xffff0000, v31
	global_load_dwordx4 v[28:31], v25, s[32:33] offset:128
	s_waitcnt lgkmcnt(10)
	v_fmac_f32_e32 v20, v148, v60
	v_fmac_f32_e32 v21, v148, v68
	v_fmac_f32_e32 v22, v148, v76
	v_fmac_f32_e32 v23, v148, v84
	v_fmac_f32_e32 v24, v148, v92
	v_fmac_f32_e32 v20, v149, v61
	v_fmac_f32_e32 v21, v149, v69
	v_fmac_f32_e32 v22, v149, v77
	v_fmac_f32_e32 v23, v149, v85
	v_fmac_f32_e32 v24, v149, v93
	v_fmac_f32_e32 v20, v150, v62
	v_fmac_f32_e32 v21, v150, v70
	v_fmac_f32_e32 v22, v150, v78
	v_fmac_f32_e32 v23, v150, v86
	v_fmac_f32_e32 v24, v150, v94
	v_fmac_f32_e32 v20, v151, v63
	v_fmac_f32_e32 v21, v151, v71
	v_fmac_f32_e32 v22, v151, v79
	v_fmac_f32_e32 v23, v151, v87
	v_fmac_f32_e32 v24, v151, v95
	v_fmac_f32_e32 v20, v152, v64
	v_fmac_f32_e32 v21, v152, v72
	v_fmac_f32_e32 v22, v152, v80
	v_fmac_f32_e32 v23, v152, v88
	v_fmac_f32_e32 v24, v152, v96
	v_fmac_f32_e32 v20, v153, v65
	v_fmac_f32_e32 v21, v153, v73
	v_fmac_f32_e32 v22, v153, v81
	v_fmac_f32_e32 v23, v153, v89
	v_fmac_f32_e32 v24, v153, v97
	v_fmac_f32_e32 v20, v154, v66
	v_fmac_f32_e32 v21, v154, v74
	v_fmac_f32_e32 v22, v154, v82
	v_fmac_f32_e32 v23, v154, v90
	v_fmac_f32_e32 v24, v154, v98
	v_fmac_f32_e32 v20, v155, v67
	v_fmac_f32_e32 v21, v155, v75
	v_fmac_f32_e32 v22, v155, v83
	v_fmac_f32_e32 v23, v155, v91
	v_fmac_f32_e32 v24, v155, v99
	ds_read_b128 v[60:63], v26 offset:320
	ds_read_b128 v[64:67], v26 offset:336
	ds_read_b128 v[68:71], v26 offset:352
	ds_read_b128 v[72:75], v26 offset:368
	ds_read_b128 v[76:79], v26 offset:384
	ds_read_b128 v[80:83], v26 offset:400
	ds_read_b128 v[84:87], v26 offset:416
	ds_read_b128 v[88:91], v26 offset:432
	ds_read_b128 v[92:95], v26 offset:448
	ds_read_b128 v[96:99], v26 offset:464
	s_waitcnt vmcnt(7)
	v_lshlrev_b32_e32 v148, 16, v32
	v_and_b32_e32 v149, 0xffff0000, v32
	v_lshlrev_b32_e32 v150, 16, v33
	v_and_b32_e32 v151, 0xffff0000, v33
	v_lshlrev_b32_e32 v152, 16, v34
	v_and_b32_e32 v153, 0xffff0000, v34
	v_lshlrev_b32_e32 v154, 16, v35
	v_and_b32_e32 v155, 0xffff0000, v35
	global_load_dwordx4 v[32:35], v25, s[32:33] offset:144
	s_waitcnt lgkmcnt(10)
; __device__ __forceinline__ void cb_item(const bf16_t* WT, int ldw, int K, int n0, const float* shift, float* out, int ostride, int lane) {
;     ...
;     for (int k8 = 0; k8 < K; k8 += 8) {
;         const u32x4 q = *(const u32x4*)(wp + k8);
;         float w[8];
; #pragma unroll
;         for (int e = 0; e < 4; ++e) { w[2 * e] = __uint_as_float(q[e] << 16); w[2 * e + 1] = __uint_as_float(q[e] & 0xffff0000u); }
; #pragma unroll
;         for (int b = 0; b < 5; ++b) { const float* sp = shift + (size_t)b * 9216 + k8;
; #pragma unroll
;             for (int e = 0; e < 8; ++e) a[b] += w[e] * sp[e]; }
;     }
	v_fmac_f32_e32 v20, v148, v100
	v_fmac_f32_e32 v21, v148, v108
	v_fmac_f32_e32 v22, v148, v116
	v_fmac_f32_e32 v23, v148, v124
	v_fmac_f32_e32 v24, v148, v132
	v_fmac_f32_e32 v20, v149, v101
	v_fmac_f32_e32 v21, v149, v109
	v_fmac_f32_e32 v22, v149, v117
	v_fmac_f32_e32 v23, v149, v125
	v_fmac_f32_e32 v24, v149, v133
	v_fmac_f32_e32 v20, v150, v102
	v_fmac_f32_e32 v21, v150, v110
	v_fmac_f32_e32 v22, v150, v118
	v_fmac_f32_e32 v23, v150, v126
	v_fmac_f32_e32 v24, v150, v134
	v_fmac_f32_e32 v20, v151, v103
	v_fmac_f32_e32 v21, v151, v111
	v_fmac_f32_e32 v22, v151, v119
	v_fmac_f32_e32 v23, v151, v127
	v_fmac_f32_e32 v24, v151, v135
	v_fmac_f32_e32 v20, v152, v104
	v_fmac_f32_e32 v21, v152, v112
	v_fmac_f32_e32 v22, v152, v120
	v_fmac_f32_e32 v23, v152, v128
	v_fmac_f32_e32 v24, v152, v136
	v_fmac_f32_e32 v20, v153, v105
	v_fmac_f32_e32 v21, v153, v113
	v_fmac_f32_e32 v22, v153, v121
	v_fmac_f32_e32 v23, v153, v129
	v_fmac_f32_e32 v24, v153, v137
	v_fmac_f32_e32 v20, v154, v106
	v_fmac_f32_e32 v21, v154, v114
	v_fmac_f32_e32 v22, v154, v122
	v_fmac_f32_e32 v23, v154, v130
	v_fmac_f32_e32 v24, v154, v138
	v_fmac_f32_e32 v20, v155, v107
	v_fmac_f32_e32 v21, v155, v115
	v_fmac_f32_e32 v22, v155, v123
	v_fmac_f32_e32 v23, v155, v131
	v_fmac_f32_e32 v24, v155, v139
	ds_read_b128 v[100:103], v26 offset:480
	ds_read_b128 v[104:107], v26 offset:496
	ds_read_b128 v[108:111], v26 offset:512
	ds_read_b128 v[112:115], v26 offset:528
	ds_read_b128 v[116:119], v26 offset:544
	ds_read_b128 v[120:123], v26 offset:560
	ds_read_b128 v[124:127], v26 offset:576
	ds_read_b128 v[128:131], v26 offset:592
	ds_read_b128 v[132:135], v26 offset:608
	ds_read_b128 v[136:139], v26 offset:624
	s_waitcnt vmcnt(7)
	v_lshlrev_b32_e32 v148, 16, v36
	v_and_b32_e32 v149, 0xffff0000, v36
	v_lshlrev_b32_e32 v150, 16, v37
	v_and_b32_e32 v151, 0xffff0000, v37
	v_lshlrev_b32_e32 v152, 16, v38
	v_and_b32_e32 v153, 0xffff0000, v38
	v_lshlrev_b32_e32 v154, 16, v39
	v_and_b32_e32 v155, 0xffff0000, v39
	global_load_dwordx4 v[36:39], v25, s[32:33] offset:160
	s_waitcnt lgkmcnt(10)
	v_fmac_f32_e32 v20, v148, v60
	v_fmac_f32_e32 v21, v148, v68
	v_fmac_f32_e32 v22, v148, v76
	v_fmac_f32_e32 v23, v148, v84
	v_fmac_f32_e32 v24, v148, v92
	v_fmac_f32_e32 v20, v149, v61
	v_fmac_f32_e32 v21, v149, v69
	v_fmac_f32_e32 v22, v149, v77
	v_fmac_f32_e32 v23, v149, v85
	v_fmac_f32_e32 v24, v149, v93
	v_fmac_f32_e32 v20, v150, v62
	v_fmac_f32_e32 v21, v150, v70
	v_fmac_f32_e32 v22, v150, v78
	v_fmac_f32_e32 v23, v150, v86
	v_fmac_f32_e32 v24, v150, v94
	v_fmac_f32_e32 v20, v151, v63
	v_fmac_f32_e32 v21, v151, v71
	v_fmac_f32_e32 v22, v151, v79
	v_fmac_f32_e32 v23, v151, v87
	v_fmac_f32_e32 v24, v151, v95
	v_fmac_f32_e32 v20, v152, v64
	v_fmac_f32_e32 v21, v152, v72
	v_fmac_f32_e32 v22, v152, v80
	v_fmac_f32_e32 v23, v152, v88
	v_fmac_f32_e32 v24, v152, v96
	v_fmac_f32_e32 v20, v153, v65
	v_fmac_f32_e32 v21, v153, v73
	v_fmac_f32_e32 v22, v153, v81
	v_fmac_f32_e32 v23, v153, v89
	v_fmac_f32_e32 v24, v153, v97
	v_fmac_f32_e32 v20, v154, v66
	v_fmac_f32_e32 v21, v154, v74
	v_fmac_f32_e32 v22, v154, v82
	v_fmac_f32_e32 v23, v154, v90
	v_fmac_f32_e32 v24, v154, v98
	v_fmac_f32_e32 v20, v155, v67
	v_fmac_f32_e32 v21, v155, v75
	v_fmac_f32_e32 v22, v155, v83
	v_fmac_f32_e32 v23, v155, v91
	v_fmac_f32_e32 v24, v155, v99
	ds_read_b128 v[60:63], v26 offset:640
	ds_read_b128 v[64:67], v26 offset:656
	ds_read_b128 v[68:71], v26 offset:672
	ds_read_b128 v[72:75], v26 offset:688
	ds_read_b128 v[76:79], v26 offset:704
	ds_read_b128 v[80:83], v26 offset:720
	ds_read_b128 v[84:87], v26 offset:736
	ds_read_b128 v[88:91], v26 offset:752
	ds_read_b128 v[92:95], v26 offset:768
	ds_read_b128 v[96:99], v26 offset:784
	s_waitcnt vmcnt(7)
	v_lshlrev_b32_e32 v148, 16, v40
	v_and_b32_e32 v149, 0xffff0000, v40
	v_lshlrev_b32_e32 v150, 16, v41
	v_and_b32_e32 v151, 0xffff0000, v41
	v_lshlrev_b32_e32 v152, 16, v42
	v_and_b32_e32 v153, 0xffff0000, v42
	v_lshlrev_b32_e32 v154, 16, v43
	v_and_b32_e32 v155, 0xffff0000, v43
	global_load_dwordx4 v[40:43], v25, s[32:33] offset:176
	s_waitcnt lgkmcnt(10)
	v_fmac_f32_e32 v20, v148, v100
	v_fmac_f32_e32 v21, v148, v108
	v_fmac_f32_e32 v22, v148, v116
	v_fmac_f32_e32 v23, v148, v124
	v_fmac_f32_e32 v24, v148, v132
	v_fmac_f32_e32 v20, v149, v101
	v_fmac_f32_e32 v21, v149, v109
	v_fmac_f32_e32 v22, v149, v117
	v_fmac_f32_e32 v23, v149, v125
	v_fmac_f32_e32 v24, v149, v133
	v_fmac_f32_e32 v20, v150, v102
	v_fmac_f32_e32 v21, v150, v110
	v_fmac_f32_e32 v22, v150, v118
	v_fmac_f32_e32 v23, v150, v126
	v_fmac_f32_e32 v24, v150, v134
	v_fmac_f32_e32 v20, v151, v103
	v_fmac_f32_e32 v21, v151, v111
	v_fmac_f32_e32 v22, v151, v119
	v_fmac_f32_e32 v23, v151, v127
	v_fmac_f32_e32 v24, v151, v135
	v_fmac_f32_e32 v20, v152, v104
	v_fmac_f32_e32 v21, v152, v112
	v_fmac_f32_e32 v22, v152, v120
	v_fmac_f32_e32 v23, v152, v128
	v_fmac_f32_e32 v24, v152, v136
	v_fmac_f32_e32 v20, v153, v105
	v_fmac_f32_e32 v21, v153, v113
	v_fmac_f32_e32 v22, v153, v121
	v_fmac_f32_e32 v23, v153, v129
	v_fmac_f32_e32 v24, v153, v137
	v_fmac_f32_e32 v20, v154, v106
	v_fmac_f32_e32 v21, v154, v114
	v_fmac_f32_e32 v22, v154, v122
	v_fmac_f32_e32 v23, v154, v130
	v_fmac_f32_e32 v24, v154, v138
	v_fmac_f32_e32 v20, v155, v107
	v_fmac_f32_e32 v21, v155, v115
	v_fmac_f32_e32 v22, v155, v123
	v_fmac_f32_e32 v23, v155, v131
	v_fmac_f32_e32 v24, v155, v139
	ds_read_b128 v[100:103], v26 offset:800
	ds_read_b128 v[104:107], v26 offset:816
	ds_read_b128 v[108:111], v26 offset:832
	ds_read_b128 v[112:115], v26 offset:848
	ds_read_b128 v[116:119], v26 offset:864
	ds_read_b128 v[120:123], v26 offset:880
	ds_read_b128 v[124:127], v26 offset:896
	ds_read_b128 v[128:131], v26 offset:912
	ds_read_b128 v[132:135], v26 offset:928
	ds_read_b128 v[136:139], v26 offset:944
	s_waitcnt vmcnt(7)
; __device__ __forceinline__ void cb_item(const bf16_t* WT, int ldw, int K, int n0, const float* shift, float* out, int ostride, int lane) {
;     ...
;     for (int k8 = 0; k8 < K; k8 += 8) {
;         const u32x4 q = *(const u32x4*)(wp + k8);
;         float w[8];
; #pragma unroll
;         for (int e = 0; e < 4; ++e) { w[2 * e] = __uint_as_float(q[e] << 16); w[2 * e + 1] = __uint_as_float(q[e] & 0xffff0000u); }
; #pragma unroll
;         for (int b = 0; b < 5; ++b) { const float* sp = shift + (size_t)b * 9216 + k8;
; #pragma unroll
;             for (int e = 0; e < 8; ++e) a[b] += w[e] * sp[e]; }
;     }
	v_lshlrev_b32_e32 v148, 16, v44
	v_and_b32_e32 v149, 0xffff0000, v44
	v_lshlrev_b32_e32 v150, 16, v45
	v_and_b32_e32 v151, 0xffff0000, v45
	v_lshlrev_b32_e32 v152, 16, v46
	v_and_b32_e32 v153, 0xffff0000, v46
	v_lshlrev_b32_e32 v154, 16, v47
	v_and_b32_e32 v155, 0xffff0000, v47
	global_load_dwordx4 v[44:47], v25, s[32:33] offset:192
	s_waitcnt lgkmcnt(10)
	v_fmac_f32_e32 v20, v148, v60
	v_fmac_f32_e32 v21, v148, v68
	v_fmac_f32_e32 v22, v148, v76
	v_fmac_f32_e32 v23, v148, v84
	v_fmac_f32_e32 v24, v148, v92
	v_fmac_f32_e32 v20, v149, v61
	v_fmac_f32_e32 v21, v149, v69
	v_fmac_f32_e32 v22, v149, v77
	v_fmac_f32_e32 v23, v149, v85
	v_fmac_f32_e32 v24, v149, v93
	v_fmac_f32_e32 v20, v150, v62
	v_fmac_f32_e32 v21, v150, v70
	v_fmac_f32_e32 v22, v150, v78
	v_fmac_f32_e32 v23, v150, v86
	v_fmac_f32_e32 v24, v150, v94
	v_fmac_f32_e32 v20, v151, v63
	v_fmac_f32_e32 v21, v151, v71
	v_fmac_f32_e32 v22, v151, v79
	v_fmac_f32_e32 v23, v151, v87
	v_fmac_f32_e32 v24, v151, v95
	v_fmac_f32_e32 v20, v152, v64
	v_fmac_f32_e32 v21, v152, v72
	v_fmac_f32_e32 v22, v152, v80
	v_fmac_f32_e32 v23, v152, v88
	v_fmac_f32_e32 v24, v152, v96
	v_fmac_f32_e32 v20, v153, v65
	v_fmac_f32_e32 v21, v153, v73
	v_fmac_f32_e32 v22, v153, v81
	v_fmac_f32_e32 v23, v153, v89
	v_fmac_f32_e32 v24, v153, v97
	v_fmac_f32_e32 v20, v154, v66
	v_fmac_f32_e32 v21, v154, v74
	v_fmac_f32_e32 v22, v154, v82
	v_fmac_f32_e32 v23, v154, v90
	v_fmac_f32_e32 v24, v154, v98
	v_fmac_f32_e32 v20, v155, v67
	v_fmac_f32_e32 v21, v155, v75
	v_fmac_f32_e32 v22, v155, v83
	v_fmac_f32_e32 v23, v155, v91
	v_fmac_f32_e32 v24, v155, v99
	ds_read_b128 v[60:63], v26 offset:960
	ds_read_b128 v[64:67], v26 offset:976
	ds_read_b128 v[68:71], v26 offset:992
	ds_read_b128 v[72:75], v26 offset:1008
	ds_read_b128 v[76:79], v26 offset:1024
	ds_read_b128 v[80:83], v26 offset:1040
	ds_read_b128 v[84:87], v26 offset:1056
	ds_read_b128 v[88:91], v26 offset:1072
	ds_read_b128 v[92:95], v26 offset:1088
	ds_read_b128 v[96:99], v26 offset:1104
	s_waitcnt vmcnt(7)
	v_lshlrev_b32_e32 v148, 16, v48
	v_and_b32_e32 v149, 0xffff0000, v48
	v_lshlrev_b32_e32 v150, 16, v49
	v_and_b32_e32 v151, 0xffff0000, v49
	v_lshlrev_b32_e32 v152, 16, v50
	v_and_b32_e32 v153, 0xffff0000, v50
	v_lshlrev_b32_e32 v154, 16, v51
	v_and_b32_e32 v155, 0xffff0000, v51
	global_load_dwordx4 v[48:51], v25, s[32:33] offset:208
	s_waitcnt lgkmcnt(10)
	v_fmac_f32_e32 v20, v148, v100
	v_fmac_f32_e32 v21, v148, v108
	v_fmac_f32_e32 v22, v148, v116
	v_fmac_f32_e32 v23, v148, v124
	v_fmac_f32_e32 v24, v148, v132
	v_fmac_f32_e32 v20, v149, v101
	v_fmac_f32_e32 v21, v149, v109
	v_fmac_f32_e32 v22, v149, v117
	v_fmac_f32_e32 v23, v149, v125
	v_fmac_f32_e32 v24, v149, v133
	v_fmac_f32_e32 v20, v150, v102
	v_fmac_f32_e32 v21, v150, v110
	v_fmac_f32_e32 v22, v150, v118
	v_fmac_f32_e32 v23, v150, v126
	v_fmac_f32_e32 v24, v150, v134
	v_fmac_f32_e32 v20, v151, v103
	v_fmac_f32_e32 v21, v151, v111
	v_fmac_f32_e32 v22, v151, v119
	v_fmac_f32_e32 v23, v151, v127
	v_fmac_f32_e32 v24, v151, v135
	v_fmac_f32_e32 v20, v152, v104
	v_fmac_f32_e32 v21, v152, v112
	v_fmac_f32_e32 v22, v152, v120
	v_fmac_f32_e32 v23, v152, v128
	v_fmac_f32_e32 v24, v152, v136
	v_fmac_f32_e32 v20, v153, v105
	v_fmac_f32_e32 v21, v153, v113
	v_fmac_f32_e32 v22, v153, v121
	v_fmac_f32_e32 v23, v153, v129
	v_fmac_f32_e32 v24, v153, v137
	v_fmac_f32_e32 v20, v154, v106
	v_fmac_f32_e32 v21, v154, v114
	v_fmac_f32_e32 v22, v154, v122
	v_fmac_f32_e32 v23, v154, v130
	v_fmac_f32_e32 v24, v154, v138
	v_fmac_f32_e32 v20, v155, v107
	v_fmac_f32_e32 v21, v155, v115
	v_fmac_f32_e32 v22, v155, v123
	v_fmac_f32_e32 v23, v155, v131
	v_fmac_f32_e32 v24, v155, v139
	ds_read_b128 v[100:103], v26 offset:1120
	ds_read_b128 v[104:107], v26 offset:1136
	ds_read_b128 v[108:111], v26 offset:1152
	ds_read_b128 v[112:115], v26 offset:1168
	ds_read_b128 v[116:119], v26 offset:1184
	ds_read_b128 v[120:123], v26 offset:1200
	ds_read_b128 v[124:127], v26 offset:1216
	ds_read_b128 v[128:131], v26 offset:1232
	ds_read_b128 v[132:135], v26 offset:1248
	ds_read_b128 v[136:139], v26 offset:1264
	s_waitcnt vmcnt(7)
	v_lshlrev_b32_e32 v148, 16, v52
	v_and_b32_e32 v149, 0xffff0000, v52
	v_lshlrev_b32_e32 v150, 16, v53
	v_and_b32_e32 v151, 0xffff0000, v53
	v_lshlrev_b32_e32 v152, 16, v54
	v_and_b32_e32 v153, 0xffff0000, v54
	v_lshlrev_b32_e32 v154, 16, v55
	v_and_b32_e32 v155, 0xffff0000, v55
	global_load_dwordx4 v[52:55], v25, s[32:33] offset:224
	s_waitcnt lgkmcnt(10)
	v_fmac_f32_e32 v20, v148, v60
	v_fmac_f32_e32 v21, v148, v68
	v_fmac_f32_e32 v22, v148, v76
	v_fmac_f32_e32 v23, v148, v84
	v_fmac_f32_e32 v24, v148, v92
	v_fmac_f32_e32 v20, v149, v61
	v_fmac_f32_e32 v21, v149, v69
	v_fmac_f32_e32 v22, v149, v77
	v_fmac_f32_e32 v23, v149, v85
	v_fmac_f32_e32 v24, v149, v93
	v_fmac_f32_e32 v20, v150, v62
	v_fmac_f32_e32 v21, v150, v70
	v_fmac_f32_e32 v22, v150, v78
	v_fmac_f32_e32 v23, v150, v86
	v_fmac_f32_e32 v24, v150, v94
	v_fmac_f32_e32 v20, v151, v63
	v_fmac_f32_e32 v21, v151, v71
	v_fmac_f32_e32 v22, v151, v79
	v_fmac_f32_e32 v23, v151, v87
	v_fmac_f32_e32 v24, v151, v95
	v_fmac_f32_e32 v20, v152, v64
	v_fmac_f32_e32 v21, v152, v72
	v_fmac_f32_e32 v22, v152, v80
	v_fmac_f32_e32 v23, v152, v88
	v_fmac_f32_e32 v24, v152, v96
	v_fmac_f32_e32 v20, v153, v65
	v_fmac_f32_e32 v21, v153, v73
	v_fmac_f32_e32 v22, v153, v81
	v_fmac_f32_e32 v23, v153, v89
	v_fmac_f32_e32 v24, v153, v97
	v_fmac_f32_e32 v20, v154, v66
	v_fmac_f32_e32 v21, v154, v74
	v_fmac_f32_e32 v22, v154, v82
	v_fmac_f32_e32 v23, v154, v90
	v_fmac_f32_e32 v24, v154, v98
	v_fmac_f32_e32 v20, v155, v67
	v_fmac_f32_e32 v21, v155, v75
	v_fmac_f32_e32 v22, v155, v83
	v_fmac_f32_e32 v23, v155, v91
	v_fmac_f32_e32 v24, v155, v99
	ds_read_b128 v[60:63], v26 offset:1280
	ds_read_b128 v[64:67], v26 offset:1296
	ds_read_b128 v[68:71], v26 offset:1312
	ds_read_b128 v[72:75], v26 offset:1328
	ds_read_b128 v[76:79], v26 offset:1344
	ds_read_b128 v[80:83], v26 offset:1360
	ds_read_b128 v[84:87], v26 offset:1376
	ds_read_b128 v[88:91], v26 offset:1392
	ds_read_b128 v[92:95], v26 offset:1408
	ds_read_b128 v[96:99], v26 offset:1424
	s_waitcnt vmcnt(7)
; __device__ __forceinline__ void cb_item(const bf16_t* WT, int ldw, int K, int n0, const float* shift, float* out, int ostride, int lane) {
;     ...
;     for (int k8 = 0; k8 < K; k8 += 8) {
;         const u32x4 q = *(const u32x4*)(wp + k8);
;         float w[8];
; #pragma unroll
;         for (int e = 0; e < 4; ++e) { w[2 * e] = __uint_as_float(q[e] << 16); w[2 * e + 1] = __uint_as_float(q[e] & 0xffff0000u); }
; #pragma unroll
;         for (int b = 0; b < 5; ++b) { const float* sp = shift + (size_t)b * 9216 + k8;
; #pragma unroll
;             for (int e = 0; e < 8; ++e) a[b] += w[e] * sp[e]; }
;     }
	v_lshlrev_b32_e32 v148, 16, v56
	v_and_b32_e32 v149, 0xffff0000, v56
	v_lshlrev_b32_e32 v150, 16, v57
	v_and_b32_e32 v151, 0xffff0000, v57
	v_lshlrev_b32_e32 v152, 16, v58
	v_and_b32_e32 v153, 0xffff0000, v58
	v_lshlrev_b32_e32 v154, 16, v59
	v_and_b32_e32 v155, 0xffff0000, v59
	global_load_dwordx4 v[56:59], v25, s[32:33] offset:240
	s_waitcnt lgkmcnt(10)
	v_fmac_f32_e32 v20, v148, v100
	v_fmac_f32_e32 v21, v148, v108
	v_fmac_f32_e32 v22, v148, v116
	v_fmac_f32_e32 v23, v148, v124
	v_fmac_f32_e32 v24, v148, v132
	v_fmac_f32_e32 v20, v149, v101
	v_fmac_f32_e32 v21, v149, v109
	v_fmac_f32_e32 v22, v149, v117
	v_fmac_f32_e32 v23, v149, v125
	v_fmac_f32_e32 v24, v149, v133
	v_fmac_f32_e32 v20, v150, v102
	v_fmac_f32_e32 v21, v150, v110
	v_fmac_f32_e32 v22, v150, v118
	v_fmac_f32_e32 v23, v150, v126
	v_fmac_f32_e32 v24, v150, v134
	v_fmac_f32_e32 v20, v151, v103
	v_fmac_f32_e32 v21, v151, v111
	v_fmac_f32_e32 v22, v151, v119
	v_fmac_f32_e32 v23, v151, v127
	v_fmac_f32_e32 v24, v151, v135
	v_fmac_f32_e32 v20, v152, v104
	v_fmac_f32_e32 v21, v152, v112
	v_fmac_f32_e32 v22, v152, v120
	v_fmac_f32_e32 v23, v152, v128
	v_fmac_f32_e32 v24, v152, v136
	v_fmac_f32_e32 v20, v153, v105
	v_fmac_f32_e32 v21, v153, v113
	v_fmac_f32_e32 v22, v153, v121
	v_fmac_f32_e32 v23, v153, v129
	v_fmac_f32_e32 v24, v153, v137
	v_fmac_f32_e32 v20, v154, v106
	v_fmac_f32_e32 v21, v154, v114
	v_fmac_f32_e32 v22, v154, v122
	v_fmac_f32_e32 v23, v154, v130
	v_fmac_f32_e32 v24, v154, v138
	v_fmac_f32_e32 v20, v155, v107
	v_fmac_f32_e32 v21, v155, v115
	v_fmac_f32_e32 v22, v155, v123
	v_fmac_f32_e32 v23, v155, v131
	v_fmac_f32_e32 v24, v155, v139
	v_add_u32_e32 v25, 0x80, v25
	v_add_u32_e32 v26, 0x500, v26
	s_add_i32 s100, s100, -1
	s_cmp_lg_u32 s100, 0
	s_cbranch_scc1 .Lcb_loop_b_0
	s_waitcnt vmcnt(0) lgkmcnt(0)
	s_add_u32 s0, s34, 0x800
	s_addc_u32 s1, s35, 0
	global_load_dwordx4 v[28:31], v19, s[0:1]
	global_load_dwordx4 v[32:35], v19, s[0:1] offset:16
	s_add_u32 s0, s0, 0x9000
	s_addc_u32 s1, s1, 0
	global_load_dwordx4 v[36:39], v19, s[0:1]
	global_load_dwordx4 v[40:43], v19, s[0:1] offset:16
	s_add_u32 s0, s0, 0x9000
	s_addc_u32 s1, s1, 0
	global_load_dwordx4 v[44:47], v19, s[0:1]
	global_load_dwordx4 v[48:51], v19, s[0:1] offset:16
	s_add_u32 s0, s0, 0x9000
	s_addc_u32 s1, s1, 0
	global_load_dwordx4 v[52:55], v19, s[0:1]
	global_load_dwordx4 v[56:59], v19, s[0:1] offset:16
	s_add_u32 s0, s0, 0x9000
	s_addc_u32 s1, s1, 0
	global_load_dwordx4 v[140:143], v19, s[0:1]
	global_load_dwordx4 v[144:147], v19, s[0:1] offset:16
	s_waitcnt vmcnt(0)
	ds_write_b128 v18, v[28:31]
	ds_write_b128 v18, v[32:35] offset:16
	ds_write_b128 v18, v[36:39] offset:32
	ds_write_b128 v18, v[40:43] offset:48
	ds_write_b128 v18, v[44:47] offset:64
	ds_write_b128 v18, v[48:51] offset:80
	ds_write_b128 v18, v[52:55] offset:96
	ds_write_b128 v18, v[56:59] offset:112
	ds_write_b128 v18, v[140:143] offset:128
	ds_write_b128 v18, v[144:147] offset:144
	s_waitcnt lgkmcnt(0)
	v_add_u32_e32 v25, 0x400, v17
	v_mov_b32_e32 v26, 0
	global_load_dwordx4 v[28:31], v25, s[32:33]
	global_load_dwordx4 v[32:35], v25, s[32:33] offset:16
	global_load_dwordx4 v[36:39], v25, s[32:33] offset:32
	global_load_dwordx4 v[40:43], v25, s[32:33] offset:48
	global_load_dwordx4 v[44:47], v25, s[32:33] offset:64
	global_load_dwordx4 v[48:51], v25, s[32:33] offset:80
	global_load_dwordx4 v[52:55], v25, s[32:33] offset:96
	global_load_dwordx4 v[56:59], v25, s[32:33] offset:112
	ds_read_b128 v[60:63], v26
	ds_read_b128 v[64:67], v26 offset:16
	ds_read_b128 v[68:71], v26 offset:32
	ds_read_b128 v[72:75], v26 offset:48
	ds_read_b128 v[76:79], v26 offset:64
	ds_read_b128 v[80:83], v26 offset:80
	ds_read_b128 v[84:87], v26 offset:96
	ds_read_b128 v[88:91], v26 offset:112
	ds_read_b128 v[92:95], v26 offset:128
	ds_read_b128 v[96:99], v26 offset:144
	s_mov_b32 s100, 8
.Lcb_loop_b_1:
	ds_read_b128 v[100:103], v26 offset:160
	ds_read_b128 v[104:107], v26 offset:176
	ds_read_b128 v[108:111], v26 offset:192
	ds_read_b128 v[112:115], v26 offset:208
	ds_read_b128 v[116:119], v26 offset:224
	ds_read_b128 v[120:123], v26 offset:240
	ds_read_b128 v[124:127], v26 offset:256
	ds_read_b128 v[128:131], v26 offset:272
	ds_read_b128 v[132:135], v26 offset:288
	ds_read_b128 v[136:139], v26 offset:304
	s_waitcnt vmcnt(7)
	v_lshlrev_b32_e32 v148, 16, v28
	v_and_b32_e32 v149, 0xffff0000, v28
	v_lshlrev_b32_e32 v150, 16, v29
	v_and_b32_e32 v151, 0xffff0000, v29
	v_lshlrev_b32_e32 v152, 16, v30
	v_and_b32_e32 v153, 0xffff0000, v30
	v_lshlrev_b32_e32 v154, 16, v31
	v_and_b32_e32 v155, 0xffff0000, v31
	global_load_dwordx4 v[28:31], v25, s[32:33] offset:128
	s_waitcnt lgkmcnt(10)
	v_fmac_f32_e32 v20, v148, v60
	v_fmac_f32_e32 v21, v148, v68
	v_fmac_f32_e32 v22, v148, v76
	v_fmac_f32_e32 v23, v148, v84
	v_fmac_f32_e32 v24, v148, v92
	v_fmac_f32_e32 v20, v149, v61
	v_fmac_f32_e32 v21, v149, v69
	v_fmac_f32_e32 v22, v149, v77
	v_fmac_f32_e32 v23, v149, v85
	v_fmac_f32_e32 v24, v149, v93
	v_fmac_f32_e32 v20, v150, v62
	v_fmac_f32_e32 v21, v150, v70
	v_fmac_f32_e32 v22, v150, v78
	v_fmac_f32_e32 v23, v150, v86
	v_fmac_f32_e32 v24, v150, v94
	v_fmac_f32_e32 v20, v151, v63
	v_fmac_f32_e32 v21, v151, v71
	v_fmac_f32_e32 v22, v151, v79
	v_fmac_f32_e32 v23, v151, v87
	v_fmac_f32_e32 v24, v151, v95
	v_fmac_f32_e32 v20, v152, v64
	v_fmac_f32_e32 v21, v152, v72
	v_fmac_f32_e32 v22, v152, v80
	v_fmac_f32_e32 v23, v152, v88
	v_fmac_f32_e32 v24, v152, v96
	v_fmac_f32_e32 v20, v153, v65
	v_fmac_f32_e32 v21, v153, v73
	v_fmac_f32_e32 v22, v153, v81
	v_fmac_f32_e32 v23, v153, v89
	v_fmac_f32_e32 v24, v153, v97
	v_fmac_f32_e32 v20, v154, v66
	v_fmac_f32_e32 v21, v154, v74
	v_fmac_f32_e32 v22, v154, v82
	v_fmac_f32_e32 v23, v154, v90
	v_fmac_f32_e32 v24, v154, v98
	v_fmac_f32_e32 v20, v155, v67
	v_fmac_f32_e32 v21, v155, v75
	v_fmac_f32_e32 v22, v155, v83
	v_fmac_f32_e32 v23, v155, v91
	v_fmac_f32_e32 v24, v155, v99
	ds_read_b128 v[60:63], v26 offset:320
	ds_read_b128 v[64:67], v26 offset:336
	ds_read_b128 v[68:71], v26 offset:352
	ds_read_b128 v[72:75], v26 offset:368
	ds_read_b128 v[76:79], v26 offset:384
	ds_read_b128 v[80:83], v26 offset:400
	ds_read_b128 v[84:87], v26 offset:416
	ds_read_b128 v[88:91], v26 offset:432
	ds_read_b128 v[92:95], v26 offset:448
	ds_read_b128 v[96:99], v26 offset:464
	s_waitcnt vmcnt(7)
; __device__ __forceinline__ void cb_item(const bf16_t* WT, int ldw, int K, int n0, const float* shift, float* out, int ostride, int lane) {
;     ...
;     for (int k8 = 0; k8 < K; k8 += 8) {
;         const u32x4 q = *(const u32x4*)(wp + k8);
;         float w[8];
; #pragma unroll
;         for (int e = 0; e < 4; ++e) { w[2 * e] = __uint_as_float(q[e] << 16); w[2 * e + 1] = __uint_as_float(q[e] & 0xffff0000u); }
; #pragma unroll
;         for (int b = 0; b < 5; ++b) { const float* sp = shift + (size_t)b * 9216 + k8;
; #pragma unroll
;             for (int e = 0; e < 8; ++e) a[b] += w[e] * sp[e]; }
;     }
	v_lshlrev_b32_e32 v148, 16, v32
	v_and_b32_e32 v149, 0xffff0000, v32
	v_lshlrev_b32_e32 v150, 16, v33
	v_and_b32_e32 v151, 0xffff0000, v33
	v_lshlrev_b32_e32 v152, 16, v34
	v_and_b32_e32 v153, 0xffff0000, v34
	v_lshlrev_b32_e32 v154, 16, v35
	v_and_b32_e32 v155, 0xffff0000, v35
	global_load_dwordx4 v[32:35], v25, s[32:33] offset:144
	s_waitcnt lgkmcnt(10)
	v_fmac_f32_e32 v20, v148, v100
	v_fmac_f32_e32 v21, v148, v108
	v_fmac_f32_e32 v22, v148, v116
	v_fmac_f32_e32 v23, v148, v124
	v_fmac_f32_e32 v24, v148, v132
	v_fmac_f32_e32 v20, v149, v101
	v_fmac_f32_e32 v21, v149, v109
	v_fmac_f32_e32 v22, v149, v117
	v_fmac_f32_e32 v23, v149, v125
	v_fmac_f32_e32 v24, v149, v133
	v_fmac_f32_e32 v20, v150, v102
	v_fmac_f32_e32 v21, v150, v110
	v_fmac_f32_e32 v22, v150, v118
	v_fmac_f32_e32 v23, v150, v126
	v_fmac_f32_e32 v24, v150, v134
	v_fmac_f32_e32 v20, v151, v103
	v_fmac_f32_e32 v21, v151, v111
	v_fmac_f32_e32 v22, v151, v119
	v_fmac_f32_e32 v23, v151, v127
	v_fmac_f32_e32 v24, v151, v135
	v_fmac_f32_e32 v20, v152, v104
	v_fmac_f32_e32 v21, v152, v112
	v_fmac_f32_e32 v22, v152, v120
	v_fmac_f32_e32 v23, v152, v128
	v_fmac_f32_e32 v24, v152, v136
	v_fmac_f32_e32 v20, v153, v105
	v_fmac_f32_e32 v21, v153, v113
	v_fmac_f32_e32 v22, v153, v121
	v_fmac_f32_e32 v23, v153, v129
	v_fmac_f32_e32 v24, v153, v137
	v_fmac_f32_e32 v20, v154, v106
	v_fmac_f32_e32 v21, v154, v114
	v_fmac_f32_e32 v22, v154, v122
	v_fmac_f32_e32 v23, v154, v130
	v_fmac_f32_e32 v24, v154, v138
	v_fmac_f32_e32 v20, v155, v107
	v_fmac_f32_e32 v21, v155, v115
	v_fmac_f32_e32 v22, v155, v123
	v_fmac_f32_e32 v23, v155, v131
	v_fmac_f32_e32 v24, v155, v139
	ds_read_b128 v[100:103], v26 offset:480
	ds_read_b128 v[104:107], v26 offset:496
	ds_read_b128 v[108:111], v26 offset:512
	ds_read_b128 v[112:115], v26 offset:528
	ds_read_b128 v[116:119], v26 offset:544
	ds_read_b128 v[120:123], v26 offset:560
	ds_read_b128 v[124:127], v26 offset:576
	ds_read_b128 v[128:131], v26 offset:592
	ds_read_b128 v[132:135], v26 offset:608
	ds_read_b128 v[136:139], v26 offset:624
	s_waitcnt vmcnt(7)
	v_lshlrev_b32_e32 v148, 16, v36
	v_and_b32_e32 v149, 0xffff0000, v36
	v_lshlrev_b32_e32 v150, 16, v37
	v_and_b32_e32 v151, 0xffff0000, v37
	v_lshlrev_b32_e32 v152, 16, v38
	v_and_b32_e32 v153, 0xffff0000, v38
	v_lshlrev_b32_e32 v154, 16, v39
	v_and_b32_e32 v155, 0xffff0000, v39
	global_load_dwordx4 v[36:39], v25, s[32:33] offset:160
	s_waitcnt lgkmcnt(10)
	v_fmac_f32_e32 v20, v148, v60
	v_fmac_f32_e32 v21, v148, v68
	v_fmac_f32_e32 v22, v148, v76
	v_fmac_f32_e32 v23, v148, v84
	v_fmac_f32_e32 v24, v148, v92
	v_fmac_f32_e32 v20, v149, v61
	v_fmac_f32_e32 v21, v149, v69
	v_fmac_f32_e32 v22, v149, v77
	v_fmac_f32_e32 v23, v149, v85
	v_fmac_f32_e32 v24, v149, v93
	v_fmac_f32_e32 v20, v150, v62
	v_fmac_f32_e32 v21, v150, v70
	v_fmac_f32_e32 v22, v150, v78
	v_fmac_f32_e32 v23, v150, v86
	v_fmac_f32_e32 v24, v150, v94
	v_fmac_f32_e32 v20, v151, v63
	v_fmac_f32_e32 v21, v151, v71
	v_fmac_f32_e32 v22, v151, v79
	v_fmac_f32_e32 v23, v151, v87
	v_fmac_f32_e32 v24, v151, v95
	v_fmac_f32_e32 v20, v152, v64
	v_fmac_f32_e32 v21, v152, v72
	v_fmac_f32_e32 v22, v152, v80
	v_fmac_f32_e32 v23, v152, v88
	v_fmac_f32_e32 v24, v152, v96
	v_fmac_f32_e32 v20, v153, v65
	v_fmac_f32_e32 v21, v153, v73
	v_fmac_f32_e32 v22, v153, v81
	v_fmac_f32_e32 v23, v153, v89
	v_fmac_f32_e32 v24, v153, v97
	v_fmac_f32_e32 v20, v154, v66
	v_fmac_f32_e32 v21, v154, v74
	v_fmac_f32_e32 v22, v154, v82
	v_fmac_f32_e32 v23, v154, v90
	v_fmac_f32_e32 v24, v154, v98
	v_fmac_f32_e32 v20, v155, v67
	v_fmac_f32_e32 v21, v155, v75
	v_fmac_f32_e32 v22, v155, v83
	v_fmac_f32_e32 v23, v155, v91
	v_fmac_f32_e32 v24, v155, v99
	ds_read_b128 v[60:63], v26 offset:640
	ds_read_b128 v[64:67], v26 offset:656
	ds_read_b128 v[68:71], v26 offset:672
	ds_read_b128 v[72:75], v26 offset:688
	ds_read_b128 v[76:79], v26 offset:704
	ds_read_b128 v[80:83], v26 offset:720
	ds_read_b128 v[84:87], v26 offset:736
	ds_read_b128 v[88:91], v26 offset:752
	ds_read_b128 v[92:95], v26 offset:768
	ds_read_b128 v[96:99], v26 offset:784
	s_waitcnt vmcnt(7)
	v_lshlrev_b32_e32 v148, 16, v40
	v_and_b32_e32 v149, 0xffff0000, v40
	v_lshlrev_b32_e32 v150, 16, v41
	v_and_b32_e32 v151, 0xffff0000, v41
	v_lshlrev_b32_e32 v152, 16, v42
	v_and_b32_e32 v153, 0xffff0000, v42
	v_lshlrev_b32_e32 v154, 16, v43
	v_and_b32_e32 v155, 0xffff0000, v43
	global_load_dwordx4 v[40:43], v25, s[32:33] offset:176
	s_waitcnt lgkmcnt(10)
	v_fmac_f32_e32 v20, v148, v100
	v_fmac_f32_e32 v21, v148, v108
	v_fmac_f32_e32 v22, v148, v116
	v_fmac_f32_e32 v23, v148, v124
	v_fmac_f32_e32 v24, v148, v132
	v_fmac_f32_e32 v20, v149, v101
	v_fmac_f32_e32 v21, v149, v109
	v_fmac_f32_e32 v22, v149, v117
	v_fmac_f32_e32 v23, v149, v125
	v_fmac_f32_e32 v24, v149, v133
	v_fmac_f32_e32 v20, v150, v102
	v_fmac_f32_e32 v21, v150, v110
	v_fmac_f32_e32 v22, v150, v118
	v_fmac_f32_e32 v23, v150, v126
	v_fmac_f32_e32 v24, v150, v134
	v_fmac_f32_e32 v20, v151, v103
	v_fmac_f32_e32 v21, v151, v111
	v_fmac_f32_e32 v22, v151, v119
	v_fmac_f32_e32 v23, v151, v127
	v_fmac_f32_e32 v24, v151, v135
	v_fmac_f32_e32 v20, v152, v104
	v_fmac_f32_e32 v21, v152, v112
	v_fmac_f32_e32 v22, v152, v120
	v_fmac_f32_e32 v23, v152, v128
	v_fmac_f32_e32 v24, v152, v136
	v_fmac_f32_e32 v20, v153, v105
	v_fmac_f32_e32 v21, v153, v113
	v_fmac_f32_e32 v22, v153, v121
	v_fmac_f32_e32 v23, v153, v129
	v_fmac_f32_e32 v24, v153, v137
	v_fmac_f32_e32 v20, v154, v106
	v_fmac_f32_e32 v21, v154, v114
	v_fmac_f32_e32 v22, v154, v122
	v_fmac_f32_e32 v23, v154, v130
	v_fmac_f32_e32 v24, v154, v138
	v_fmac_f32_e32 v20, v155, v107
	v_fmac_f32_e32 v21, v155, v115
	v_fmac_f32_e32 v22, v155, v123
	v_fmac_f32_e32 v23, v155, v131
	v_fmac_f32_e32 v24, v155, v139
	ds_read_b128 v[100:103], v26 offset:800
	ds_read_b128 v[104:107], v26 offset:816
	ds_read_b128 v[108:111], v26 offset:832
	ds_read_b128 v[112:115], v26 offset:848
	ds_read_b128 v[116:119], v26 offset:864
	ds_read_b128 v[120:123], v26 offset:880
	ds_read_b128 v[124:127], v26 offset:896
	ds_read_b128 v[128:131], v26 offset:912
	ds_read_b128 v[132:135], v26 offset:928
	ds_read_b128 v[136:139], v26 offset:944
	s_waitcnt vmcnt(7)
; __device__ __forceinline__ void cb_item(const bf16_t* WT, int ldw, int K, int n0, const float* shift, float* out, int ostride, int lane) {
;     ...
;     for (int k8 = 0; k8 < K; k8 += 8) {
;         const u32x4 q = *(const u32x4*)(wp + k8);
;         float w[8];
; #pragma unroll
;         for (int e = 0; e < 4; ++e) { w[2 * e] = __uint_as_float(q[e] << 16); w[2 * e + 1] = __uint_as_float(q[e] & 0xffff0000u); }
; #pragma unroll
;         for (int b = 0; b < 5; ++b) { const float* sp = shift + (size_t)b * 9216 + k8;
; #pragma unroll
;             for (int e = 0; e < 8; ++e) a[b] += w[e] * sp[e]; }
;     }
	v_lshlrev_b32_e32 v148, 16, v44
	v_and_b32_e32 v149, 0xffff0000, v44
	v_lshlrev_b32_e32 v150, 16, v45
	v_and_b32_e32 v151, 0xffff0000, v45
	v_lshlrev_b32_e32 v152, 16, v46
	v_and_b32_e32 v153, 0xffff0000, v46
	v_lshlrev_b32_e32 v154, 16, v47
	v_and_b32_e32 v155, 0xffff0000, v47
	global_load_dwordx4 v[44:47], v25, s[32:33] offset:192
	s_waitcnt lgkmcnt(10)
	v_fmac_f32_e32 v20, v148, v60
	v_fmac_f32_e32 v21, v148, v68
	v_fmac_f32_e32 v22, v148, v76
	v_fmac_f32_e32 v23, v148, v84
	v_fmac_f32_e32 v24, v148, v92
	v_fmac_f32_e32 v20, v149, v61
	v_fmac_f32_e32 v21, v149, v69
	v_fmac_f32_e32 v22, v149, v77
	v_fmac_f32_e32 v23, v149, v85
	v_fmac_f32_e32 v24, v149, v93
	v_fmac_f32_e32 v20, v150, v62
	v_fmac_f32_e32 v21, v150, v70
	v_fmac_f32_e32 v22, v150, v78
	v_fmac_f32_e32 v23, v150, v86
	v_fmac_f32_e32 v24, v150, v94
	v_fmac_f32_e32 v20, v151, v63
	v_fmac_f32_e32 v21, v151, v71
	v_fmac_f32_e32 v22, v151, v79
	v_fmac_f32_e32 v23, v151, v87
	v_fmac_f32_e32 v24, v151, v95
	v_fmac_f32_e32 v20, v152, v64
	v_fmac_f32_e32 v21, v152, v72
	v_fmac_f32_e32 v22, v152, v80
	v_fmac_f32_e32 v23, v152, v88
	v_fmac_f32_e32 v24, v152, v96
	v_fmac_f32_e32 v20, v153, v65
	v_fmac_f32_e32 v21, v153, v73
	v_fmac_f32_e32 v22, v153, v81
	v_fmac_f32_e32 v23, v153, v89
	v_fmac_f32_e32 v24, v153, v97
	v_fmac_f32_e32 v20, v154, v66
	v_fmac_f32_e32 v21, v154, v74
	v_fmac_f32_e32 v22, v154, v82
	v_fmac_f32_e32 v23, v154, v90
	v_fmac_f32_e32 v24, v154, v98
	v_fmac_f32_e32 v20, v155, v67
	v_fmac_f32_e32 v21, v155, v75
	v_fmac_f32_e32 v22, v155, v83
	v_fmac_f32_e32 v23, v155, v91
	v_fmac_f32_e32 v24, v155, v99
	ds_read_b128 v[60:63], v26 offset:960
	ds_read_b128 v[64:67], v26 offset:976
	ds_read_b128 v[68:71], v26 offset:992
	ds_read_b128 v[72:75], v26 offset:1008
	ds_read_b128 v[76:79], v26 offset:1024
	ds_read_b128 v[80:83], v26 offset:1040
	ds_read_b128 v[84:87], v26 offset:1056
	ds_read_b128 v[88:91], v26 offset:1072
	ds_read_b128 v[92:95], v26 offset:1088
	ds_read_b128 v[96:99], v26 offset:1104
	s_waitcnt vmcnt(7)
	v_lshlrev_b32_e32 v148, 16, v48
	v_and_b32_e32 v149, 0xffff0000, v48
	v_lshlrev_b32_e32 v150, 16, v49
	v_and_b32_e32 v151, 0xffff0000, v49
	v_lshlrev_b32_e32 v152, 16, v50
	v_and_b32_e32 v153, 0xffff0000, v50
	v_lshlrev_b32_e32 v154, 16, v51
	v_and_b32_e32 v155, 0xffff0000, v51
	global_load_dwordx4 v[48:51], v25, s[32:33] offset:208
	s_waitcnt lgkmcnt(10)
	v_fmac_f32_e32 v20, v148, v100
	v_fmac_f32_e32 v21, v148, v108
	v_fmac_f32_e32 v22, v148, v116
	v_fmac_f32_e32 v23, v148, v124
	v_fmac_f32_e32 v24, v148, v132
	v_fmac_f32_e32 v20, v149, v101
	v_fmac_f32_e32 v21, v149, v109
	v_fmac_f32_e32 v22, v149, v117
	v_fmac_f32_e32 v23, v149, v125
	v_fmac_f32_e32 v24, v149, v133
	v_fmac_f32_e32 v20, v150, v102
	v_fmac_f32_e32 v21, v150, v110
	v_fmac_f32_e32 v22, v150, v118
	v_fmac_f32_e32 v23, v150, v126
	v_fmac_f32_e32 v24, v150, v134
	v_fmac_f32_e32 v20, v151, v103
	v_fmac_f32_e32 v21, v151, v111
	v_fmac_f32_e32 v22, v151, v119
	v_fmac_f32_e32 v23, v151, v127
	v_fmac_f32_e32 v24, v151, v135
	v_fmac_f32_e32 v20, v152, v104
	v_fmac_f32_e32 v21, v152, v112
	v_fmac_f32_e32 v22, v152, v120
	v_fmac_f32_e32 v23, v152, v128
	v_fmac_f32_e32 v24, v152, v136
	v_fmac_f32_e32 v20, v153, v105
	v_fmac_f32_e32 v21, v153, v113
	v_fmac_f32_e32 v22, v153, v121
	v_fmac_f32_e32 v23, v153, v129
	v_fmac_f32_e32 v24, v153, v137
	v_fmac_f32_e32 v20, v154, v106
	v_fmac_f32_e32 v21, v154, v114
	v_fmac_f32_e32 v22, v154, v122
	v_fmac_f32_e32 v23, v154, v130
	v_fmac_f32_e32 v24, v154, v138
	v_fmac_f32_e32 v20, v155, v107
	v_fmac_f32_e32 v21, v155, v115
	v_fmac_f32_e32 v22, v155, v123
	v_fmac_f32_e32 v23, v155, v131
	v_fmac_f32_e32 v24, v155, v139
	ds_read_b128 v[100:103], v26 offset:1120
	ds_read_b128 v[104:107], v26 offset:1136
	ds_read_b128 v[108:111], v26 offset:1152
	ds_read_b128 v[112:115], v26 offset:1168
	ds_read_b128 v[116:119], v26 offset:1184
	ds_read_b128 v[120:123], v26 offset:1200
	ds_read_b128 v[124:127], v26 offset:1216
	ds_read_b128 v[128:131], v26 offset:1232
	ds_read_b128 v[132:135], v26 offset:1248
	ds_read_b128 v[136:139], v26 offset:1264
	s_waitcnt vmcnt(7)
	v_lshlrev_b32_e32 v148, 16, v52
	v_and_b32_e32 v149, 0xffff0000, v52
	v_lshlrev_b32_e32 v150, 16, v53
	v_and_b32_e32 v151, 0xffff0000, v53
	v_lshlrev_b32_e32 v152, 16, v54
	v_and_b32_e32 v153, 0xffff0000, v54
	v_lshlrev_b32_e32 v154, 16, v55
	v_and_b32_e32 v155, 0xffff0000, v55
	global_load_dwordx4 v[52:55], v25, s[32:33] offset:224
	s_waitcnt lgkmcnt(10)
	v_fmac_f32_e32 v20, v148, v60
	v_fmac_f32_e32 v21, v148, v68
	v_fmac_f32_e32 v22, v148, v76
	v_fmac_f32_e32 v23, v148, v84
	v_fmac_f32_e32 v24, v148, v92
	v_fmac_f32_e32 v20, v149, v61
	v_fmac_f32_e32 v21, v149, v69
	v_fmac_f32_e32 v22, v149, v77
	v_fmac_f32_e32 v23, v149, v85
	v_fmac_f32_e32 v24, v149, v93
	v_fmac_f32_e32 v20, v150, v62
	v_fmac_f32_e32 v21, v150, v70
	v_fmac_f32_e32 v22, v150, v78
	v_fmac_f32_e32 v23, v150, v86
	v_fmac_f32_e32 v24, v150, v94
	v_fmac_f32_e32 v20, v151, v63
	v_fmac_f32_e32 v21, v151, v71
	v_fmac_f32_e32 v22, v151, v79
	v_fmac_f32_e32 v23, v151, v87
	v_fmac_f32_e32 v24, v151, v95
	v_fmac_f32_e32 v20, v152, v64
	v_fmac_f32_e32 v21, v152, v72
	v_fmac_f32_e32 v22, v152, v80
	v_fmac_f32_e32 v23, v152, v88
	v_fmac_f32_e32 v24, v152, v96
	v_fmac_f32_e32 v20, v153, v65
	v_fmac_f32_e32 v21, v153, v73
	v_fmac_f32_e32 v22, v153, v81
	v_fmac_f32_e32 v23, v153, v89
	v_fmac_f32_e32 v24, v153, v97
	v_fmac_f32_e32 v20, v154, v66
	v_fmac_f32_e32 v21, v154, v74
	v_fmac_f32_e32 v22, v154, v82
	v_fmac_f32_e32 v23, v154, v90
	v_fmac_f32_e32 v24, v154, v98
	v_fmac_f32_e32 v20, v155, v67
	v_fmac_f32_e32 v21, v155, v75
	v_fmac_f32_e32 v22, v155, v83
	v_fmac_f32_e32 v23, v155, v91
	v_fmac_f32_e32 v24, v155, v99
	ds_read_b128 v[60:63], v26 offset:1280
	ds_read_b128 v[64:67], v26 offset:1296
	ds_read_b128 v[68:71], v26 offset:1312
	ds_read_b128 v[72:75], v26 offset:1328
	ds_read_b128 v[76:79], v26 offset:1344
	ds_read_b128 v[80:83], v26 offset:1360
	ds_read_b128 v[84:87], v26 offset:1376
	ds_read_b128 v[88:91], v26 offset:1392
	ds_read_b128 v[92:95], v26 offset:1408
	ds_read_b128 v[96:99], v26 offset:1424
	s_waitcnt vmcnt(7)
; #define LAS __attribute__((address_space(3)))
; __device__ __forceinline__ unsigned cvt_pk_bf16(float lo, float hi) { unsigned r; asm volatile("v_cvt_pk_bf16_f32 %0, %1, %2" : "=v"(r) : "v"(lo), "v"(hi)); return r; }
; #define ST16(grp, p, v) do { if ((NTG >> (grp)) & 1) NT16(p, v); else PL16(p, v); } while (0)
; __device__ __forceinline__ void transpose_item(const float* W, int K, int N, bf16_t* WT, int n0src, int n0dst, int k0, LAS float* scr, int lane) {
;     float v[32];
; #pragma unroll
;     for (int i = 0; i < 32; ++i) { const int kk = 2 * i + (lane >> 5); v[i] = W[(size_t)(k0 + kk) * N + n0src + (lane & 31)]; }
; #pragma unroll
;     for (int i = 0; i < 32; ++i) { const int kk = 2 * i + (lane >> 5); scr[kk * 33 + (lane & 31)] = v[i]; }
;     asm volatile("s_waitcnt lgkmcnt(0)" ::: "memory");
;     const int c = lane & 7;
; #pragma unroll
;     for (int j = 0; j < 4; ++j) { const int n = (lane >> 3) + 8 * j; const LAS float* s = scr + (8 * c) * 33 + n;
;         u32x4 o; o.x = cvt_pk_bf16(s[0 * 33], s[1 * 33]); o.y = cvt_pk_bf16(s[2 * 33], s[3 * 33]); o.z = cvt_pk_bf16(s[4 * 33], s[5 * 33]); o.w = cvt_pk_bf16(s[6 * 33], s[7 * 33]);
;         ST16(6, WT + (size_t)(n0dst + n) * K + k0 + 8 * c, o); }
;     asm volatile("s_waitcnt lgkmcnt(0)" ::: "memory");
; }
; __device__ __forceinline__ void cb_item(const bf16_t* WT, int ldw, int K, int n0, const float* shift, float* out, int ostride, int lane) {
;     ...
; #pragma unroll
;     for (int b = 0; b < 5; ++b) out[(size_t)b * ostride + n0 + lane] = a[b];
	v_lshlrev_b32_e32 v148, 16, v56
	v_and_b32_e32 v149, 0xffff0000, v56
	v_lshlrev_b32_e32 v150, 16, v57
	v_and_b32_e32 v151, 0xffff0000, v57
	v_lshlrev_b32_e32 v152, 16, v58
	v_and_b32_e32 v153, 0xffff0000, v58
	v_lshlrev_b32_e32 v154, 16, v59
	v_and_b32_e32 v155, 0xffff0000, v59
	global_load_dwordx4 v[56:59], v25, s[32:33] offset:240
	s_waitcnt lgkmcnt(10)
	v_fmac_f32_e32 v20, v148, v100
	v_fmac_f32_e32 v21, v148, v108
	v_fmac_f32_e32 v22, v148, v116
	v_fmac_f32_e32 v23, v148, v124
	v_fmac_f32_e32 v24, v148, v132
	v_fmac_f32_e32 v20, v149, v101
	v_fmac_f32_e32 v21, v149, v109
	v_fmac_f32_e32 v22, v149, v117
	v_fmac_f32_e32 v23, v149, v125
	v_fmac_f32_e32 v24, v149, v133
	v_fmac_f32_e32 v20, v150, v102
	v_fmac_f32_e32 v21, v150, v110
	v_fmac_f32_e32 v22, v150, v118
	v_fmac_f32_e32 v23, v150, v126
	v_fmac_f32_e32 v24, v150, v134
	v_fmac_f32_e32 v20, v151, v103
	v_fmac_f32_e32 v21, v151, v111
	v_fmac_f32_e32 v22, v151, v119
	v_fmac_f32_e32 v23, v151, v127
	v_fmac_f32_e32 v24, v151, v135
	v_fmac_f32_e32 v20, v152, v104
	v_fmac_f32_e32 v21, v152, v112
	v_fmac_f32_e32 v22, v152, v120
	v_fmac_f32_e32 v23, v152, v128
	v_fmac_f32_e32 v24, v152, v136
	v_fmac_f32_e32 v20, v153, v105
	v_fmac_f32_e32 v21, v153, v113
	v_fmac_f32_e32 v22, v153, v121
	v_fmac_f32_e32 v23, v153, v129
	v_fmac_f32_e32 v24, v153, v137
	v_fmac_f32_e32 v20, v154, v106
	v_fmac_f32_e32 v21, v154, v114
	v_fmac_f32_e32 v22, v154, v122
	v_fmac_f32_e32 v23, v154, v130
	v_fmac_f32_e32 v24, v154, v138
	v_fmac_f32_e32 v20, v155, v107
	v_fmac_f32_e32 v21, v155, v115
	v_fmac_f32_e32 v22, v155, v123
	v_fmac_f32_e32 v23, v155, v131
	v_fmac_f32_e32 v24, v155, v139
	v_add_u32_e32 v25, 0x80, v25
	v_add_u32_e32 v26, 0x500, v26
	s_add_i32 s100, s100, -1
	s_cmp_lg_u32 s100, 0
	s_cbranch_scc1 .Lcb_loop_b_1
	s_waitcnt vmcnt(0) lgkmcnt(0)
	s_lshl_b32 s0, s37, 8
	s_add_u32 s0, s0, 0x152800
	s_add_u32 s0, s76, s0
	s_addc_u32 s1, s77, 0
	v_lshlrev_b32_e32 v27, 2, v16
	global_store_dword v27, v20, s[0:1]
	s_add_u32 s0, s0, 0x5800
	s_addc_u32 s1, s1, 0
	global_store_dword v27, v21, s[0:1]
	s_add_u32 s0, s0, 0x5800
	s_addc_u32 s1, s1, 0
	global_store_dword v27, v22, s[0:1]
	s_add_u32 s0, s0, 0x5800
	s_addc_u32 s1, s1, 0
	global_store_dword v27, v23, s[0:1]
	s_add_u32 s0, s0, 0x5800
	s_addc_u32 s1, s1, 0
	global_store_dword v27, v24, s[0:1]
	s_branch .Ltr_fin_b
.Ltr_w17_b:
	s_mul_i32 s36, s37, 7
	s_add_i32 s36, s36, s99
	s_add_i32 s36, s36, -1
	s_lshl_b32 s99, s99, 14
	v_and_b32_e32 v16, 63, v176
	v_and_b32_e32 v17, 31, v16
	v_lshrrev_b32_e32 v18, 5, v16
	v_mul_u32_u24_e32 v19, 0x84, v18
	v_lshl_add_u32 v19, v17, 2, v19
	v_add_u32_e32 v19, s99, v19
	v_and_b32_e32 v20, 7, v16
	v_lshrrev_b32_e32 v21, 3, v16
	v_mul_u32_u24_e32 v22, 0x420, v20
	v_lshl_add_u32 v22, v21, 2, v22
	v_add_u32_e32 v22, s99, v22
	v_lshlrev_b32_e32 v23, 12, v18
	v_lshl_add_u32 v23, v17, 2, v23
	v_mul_u32_u24_e32 v24, 0x1600, v21
	v_lshl_add_u32 v24, v20, 4, v24
	v_readlane_b32 s32, v253, 0
	v_readlane_b32 s33, v253, 1
	s_add_u32 s32, s32, 0x1600000
	s_addc_u32 s33, s33, 0
	s_add_u32 s34, s76, 0x3900000
	s_addc_u32 s35, s77, 0
	s_mov_b32 s98, s36
	s_cmpk_ge_u32 s98, 0x580
	s_cbranch_scc1 .Ltr_end_b0
; #define LAS __attribute__((address_space(3)))
; __device__ __forceinline__ unsigned cvt_pk_bf16(float lo, float hi) { unsigned r; asm volatile("v_cvt_pk_bf16_f32 %0, %1, %2" : "=v"(r) : "v"(lo), "v"(hi)); return r; }
; #define ST16(grp, p, v) do { if ((NTG >> (grp)) & 1) NT16(p, v); else PL16(p, v); } while (0)
; __device__ __forceinline__ void transpose_item(const float* W, int K, int N, bf16_t* WT, int n0src, int n0dst, int k0, LAS float* scr, int lane) {
;     float v[32];
; #pragma unroll
;     for (int i = 0; i < 32; ++i) { const int kk = 2 * i + (lane >> 5); v[i] = W[(size_t)(k0 + kk) * N + n0src + (lane & 31)]; }
; #pragma unroll
;     for (int i = 0; i < 32; ++i) { const int kk = 2 * i + (lane >> 5); scr[kk * 33 + (lane & 31)] = v[i]; }
;     asm volatile("s_waitcnt lgkmcnt(0)" ::: "memory");
;     const int c = lane & 7;
; #pragma unroll
;     for (int j = 0; j < 4; ++j) { const int n = (lane >> 3) + 8 * j; const LAS float* s = scr + (8 * c) * 33 + n;
;         u32x4 o; o.x = cvt_pk_bf16(s[0 * 33], s[1 * 33]); o.y = cvt_pk_bf16(s[2 * 33], s[3 * 33]); o.z = cvt_pk_bf16(s[4 * 33], s[5 * 33]); o.w = cvt_pk_bf16(s[6 * 33], s[7 * 33]);
;         ST16(6, WT + (size_t)(n0dst + n) * K + k0 + 8 * c, o); }
;     asm volatile("s_waitcnt lgkmcnt(0)" ::: "memory");
; }
; __device__ __forceinline__ void prologue(const Params& p, LAS unsigned char* lds) {
;     ...
;             if (r < 4 * I_W2) { const int mi = r / I_W2; r -= mi * I_W2; const int kb = r / 32, nb = r % 32;
;                 transpose_item(p.in[I_FFNWOUT] + (size_t)mi * DFF * D, DFF, D, (bf16_t*)(ws + WS_W2T + mi * SZ_W2T), nb * 32, nb * 32, kb * 64, scr, lane); continue; }
.Ltr_loop_b0:
	s_lshr_b32 s100, s98, 5
	s_and_b32 s101, s98, 31
	s_lshl_b32 s0, s100, 18
	s_lshl_b32 s1, s101, 7
	s_add_u32 s0, s0, s1
	s_add_u32 s0, s32, s0
	s_addc_u32 s1, s33, 0
	global_load_dword v32, v23, s[0:1] nt
	s_add_u32 s0, s0, 0x2000
	s_addc_u32 s1, s1, 0
	global_load_dword v33, v23, s[0:1] nt
	s_add_u32 s0, s0, 0x2000
	s_addc_u32 s1, s1, 0
	global_load_dword v34, v23, s[0:1] nt
	s_add_u32 s0, s0, 0x2000
	s_addc_u32 s1, s1, 0
	global_load_dword v35, v23, s[0:1] nt
	s_add_u32 s0, s0, 0x2000
	s_addc_u32 s1, s1, 0
	global_load_dword v36, v23, s[0:1] nt
	s_add_u32 s0, s0, 0x2000
	s_addc_u32 s1, s1, 0
	global_load_dword v37, v23, s[0:1] nt
	s_add_u32 s0, s0, 0x2000
	s_addc_u32 s1, s1, 0
	global_load_dword v38, v23, s[0:1] nt
	s_add_u32 s0, s0, 0x2000
	s_addc_u32 s1, s1, 0
	global_load_dword v39, v23, s[0:1] nt
	s_add_u32 s0, s0, 0x2000
	s_addc_u32 s1, s1, 0
	global_load_dword v40, v23, s[0:1] nt
	s_add_u32 s0, s0, 0x2000
	s_addc_u32 s1, s1, 0
	global_load_dword v41, v23, s[0:1] nt
	s_add_u32 s0, s0, 0x2000
	s_addc_u32 s1, s1, 0
	global_load_dword v42, v23, s[0:1] nt
	s_add_u32 s0, s0, 0x2000
	s_addc_u32 s1, s1, 0
	global_load_dword v43, v23, s[0:1] nt
	s_add_u32 s0, s0, 0x2000
	s_addc_u32 s1, s1, 0
	global_load_dword v44, v23, s[0:1] nt
	s_add_u32 s0, s0, 0x2000
	s_addc_u32 s1, s1, 0
	global_load_dword v45, v23, s[0:1] nt
	s_add_u32 s0, s0, 0x2000
	s_addc_u32 s1, s1, 0
	global_load_dword v46, v23, s[0:1] nt
	s_add_u32 s0, s0, 0x2000
	s_addc_u32 s1, s1, 0
	global_load_dword v47, v23, s[0:1] nt
	s_add_u32 s0, s0, 0x2000
	s_addc_u32 s1, s1, 0
	global_load_dword v48, v23, s[0:1] nt
	s_add_u32 s0, s0, 0x2000
	s_addc_u32 s1, s1, 0
	global_load_dword v49, v23, s[0:1] nt
	s_add_u32 s0, s0, 0x2000
	s_addc_u32 s1, s1, 0
	global_load_dword v50, v23, s[0:1] nt
	s_add_u32 s0, s0, 0x2000
	s_addc_u32 s1, s1, 0
	global_load_dword v51, v23, s[0:1] nt
	s_add_u32 s0, s0, 0x2000
	s_addc_u32 s1, s1, 0
	global_load_dword v52, v23, s[0:1] nt
	s_add_u32 s0, s0, 0x2000
	s_addc_u32 s1, s1, 0
	global_load_dword v53, v23, s[0:1] nt
	s_add_u32 s0, s0, 0x2000
	s_addc_u32 s1, s1, 0
	global_load_dword v54, v23, s[0:1] nt
	s_add_u32 s0, s0, 0x2000
	s_addc_u32 s1, s1, 0
	global_load_dword v55, v23, s[0:1] nt
	s_add_u32 s0, s0, 0x2000
	s_addc_u32 s1, s1, 0
	global_load_dword v56, v23, s[0:1] nt
	s_add_u32 s0, s0, 0x2000
	s_addc_u32 s1, s1, 0
	global_load_dword v57, v23, s[0:1] nt
	s_add_u32 s0, s0, 0x2000
	s_addc_u32 s1, s1, 0
	global_load_dword v58, v23, s[0:1] nt
	s_add_u32 s0, s0, 0x2000
	s_addc_u32 s1, s1, 0
	global_load_dword v59, v23, s[0:1] nt
	s_add_u32 s0, s0, 0x2000
	s_addc_u32 s1, s1, 0
	global_load_dword v60, v23, s[0:1] nt
	s_add_u32 s0, s0, 0x2000
	s_addc_u32 s1, s1, 0
	global_load_dword v61, v23, s[0:1] nt
	s_add_u32 s0, s0, 0x2000
	s_addc_u32 s1, s1, 0
	global_load_dword v62, v23, s[0:1] nt
	s_add_u32 s0, s0, 0x2000
	s_addc_u32 s1, s1, 0
	global_load_dword v63, v23, s[0:1] nt
	s_waitcnt vmcnt(31)
	ds_write_b32 v19, v32
	s_waitcnt vmcnt(30)
	ds_write_b32 v19, v33 offset:264
	s_waitcnt vmcnt(29)
	ds_write_b32 v19, v34 offset:528
	s_waitcnt vmcnt(28)
	ds_write_b32 v19, v35 offset:792
	s_waitcnt vmcnt(27)
	ds_write_b32 v19, v36 offset:1056
	s_waitcnt vmcnt(26)
	ds_write_b32 v19, v37 offset:1320
	s_waitcnt vmcnt(25)
	ds_write_b32 v19, v38 offset:1584
	s_waitcnt vmcnt(24)
	ds_write_b32 v19, v39 offset:1848
	s_waitcnt vmcnt(23)
	ds_write_b32 v19, v40 offset:2112
	s_waitcnt vmcnt(22)
	ds_write_b32 v19, v41 offset:2376
	s_waitcnt vmcnt(21)
	ds_write_b32 v19, v42 offset:2640
	s_waitcnt vmcnt(20)
	ds_write_b32 v19, v43 offset:2904
	s_waitcnt vmcnt(19)
	ds_write_b32 v19, v44 offset:3168
	s_waitcnt vmcnt(18)
	ds_write_b32 v19, v45 offset:3432
	s_waitcnt vmcnt(17)
	ds_write_b32 v19, v46 offset:3696
	s_waitcnt vmcnt(16)
	ds_write_b32 v19, v47 offset:3960
	s_waitcnt vmcnt(15)
	ds_write_b32 v19, v48 offset:4224
	s_waitcnt vmcnt(14)
	ds_write_b32 v19, v49 offset:4488
	s_waitcnt vmcnt(13)
	ds_write_b32 v19, v50 offset:4752
	s_waitcnt vmcnt(12)
	ds_write_b32 v19, v51 offset:5016
	s_waitcnt vmcnt(11)
	ds_write_b32 v19, v52 offset:5280
	s_waitcnt vmcnt(10)
	ds_write_b32 v19, v53 offset:5544
	s_waitcnt vmcnt(9)
	ds_write_b32 v19, v54 offset:5808
	s_waitcnt vmcnt(8)
	ds_write_b32 v19, v55 offset:6072
	s_waitcnt vmcnt(7)
	ds_write_b32 v19, v56 offset:6336
	s_waitcnt vmcnt(6)
	ds_write_b32 v19, v57 offset:6600
	s_waitcnt vmcnt(5)
	ds_write_b32 v19, v58 offset:6864
	s_waitcnt vmcnt(4)
	ds_write_b32 v19, v59 offset:7128
	s_waitcnt vmcnt(3)
	ds_write_b32 v19, v60 offset:7392
	s_waitcnt vmcnt(2)
	ds_write_b32 v19, v61 offset:7656
	s_waitcnt vmcnt(1)
	ds_write_b32 v19, v62 offset:7920
	s_waitcnt vmcnt(0)
	ds_write_b32 v19, v63 offset:8184
	s_mul_i32 s0, s101, 0x2c000
	s_lshl_b32 s1, s100, 7
	s_add_u32 s0, s0, s1
	s_add_u32 s0, s34, s0
	s_addc_u32 s1, s35, 0
	s_waitcnt lgkmcnt(0)
	ds_read_b32 v64, v22
	ds_read_b32 v65, v22 offset:132
	ds_read_b32 v66, v22 offset:264
	ds_read_b32 v67, v22 offset:396
	ds_read_b32 v68, v22 offset:528
	ds_read_b32 v69, v22 offset:660
	ds_read_b32 v70, v22 offset:792
	ds_read_b32 v71, v22 offset:924
	ds_read_b32 v72, v22 offset:32
	ds_read_b32 v73, v22 offset:164
	ds_read_b32 v74, v22 offset:296
	ds_read_b32 v75, v22 offset:428
	ds_read_b32 v76, v22 offset:560
	ds_read_b32 v77, v22 offset:692
	ds_read_b32 v78, v22 offset:824
	ds_read_b32 v79, v22 offset:956
	ds_read_b32 v80, v22 offset:64
	ds_read_b32 v81, v22 offset:196
	ds_read_b32 v82, v22 offset:328
	ds_read_b32 v83, v22 offset:460
	ds_read_b32 v84, v22 offset:592
	ds_read_b32 v85, v22 offset:724
	ds_read_b32 v86, v22 offset:856
	ds_read_b32 v87, v22 offset:988
	ds_read_b32 v88, v22 offset:96
	ds_read_b32 v89, v22 offset:228
	ds_read_b32 v90, v22 offset:360
	ds_read_b32 v91, v22 offset:492
	ds_read_b32 v92, v22 offset:624
	ds_read_b32 v93, v22 offset:756
	ds_read_b32 v94, v22 offset:888
	ds_read_b32 v95, v22 offset:1020
	s_waitcnt lgkmcnt(15)
	v_cvt_pk_bf16_f32 v96, v64, v65
	v_cvt_pk_bf16_f32 v97, v66, v67
	v_cvt_pk_bf16_f32 v98, v68, v69
	v_cvt_pk_bf16_f32 v99, v70, v71
	global_store_dwordx4 v24, v[96:99], s[0:1]
	s_add_u32 s0, s0, 0xb000
	s_addc_u32 s1, s1, 0
	s_waitcnt lgkmcnt(15)
	v_cvt_pk_bf16_f32 v100, v72, v73
	v_cvt_pk_bf16_f32 v101, v74, v75
	v_cvt_pk_bf16_f32 v102, v76, v77
	v_cvt_pk_bf16_f32 v103, v78, v79
	global_store_dwordx4 v24, v[100:103], s[0:1]
	s_add_u32 s0, s0, 0xb000
	s_addc_u32 s1, s1, 0
	s_waitcnt lgkmcnt(8)
	v_cvt_pk_bf16_f32 v104, v80, v81
	v_cvt_pk_bf16_f32 v105, v82, v83
	v_cvt_pk_bf16_f32 v106, v84, v85
	v_cvt_pk_bf16_f32 v107, v86, v87
	global_store_dwordx4 v24, v[104:107], s[0:1]
	s_add_u32 s0, s0, 0xb000
	s_addc_u32 s1, s1, 0
	s_waitcnt lgkmcnt(0)
	v_cvt_pk_bf16_f32 v108, v88, v89
	v_cvt_pk_bf16_f32 v109, v90, v91
	v_cvt_pk_bf16_f32 v110, v92, v93
	v_cvt_pk_bf16_f32 v111, v94, v95
	global_store_dwordx4 v24, v[108:111], s[0:1]
	s_add_i32 s98, s98, 0x380
	s_cmpk_lt_u32 s98, 0x580
	s_cbranch_scc1 .Ltr_loop_b0

; #define LAS __attribute__((address_space(3)))
; __device__ __forceinline__ void transpose_item(const float* W, int K, int N, bf16_t* WT, int n0src, int n0dst, int k0, LAS float* scr, int lane) {
;     float v[32];
; #pragma unroll
;     for (int i = 0; i < 32; ++i) { const int kk = 2 * i + (lane >> 5); v[i] = W[(size_t)(k0 + kk) * N + n0src + (lane & 31)]; }
; #pragma unroll
;     for (int i = 0; i < 32; ++i) { const int kk = 2 * i + (lane >> 5); scr[kk * 33 + (lane & 31)] = v[i]; }
;     asm volatile("s_waitcnt lgkmcnt(0)" ::: "memory");
;     const int c = lane & 7;
; __device__ __forceinline__ void prologue(const Params& p, LAS unsigned char* lds) {
;     ...
;         for (int it = gw; it < NITEMS; it += NGW) {
;             int r = it;
;             if (r < 4 * I_W1) { const int mi = r / I_W1; r -= mi * I_W1; const int kb = r / 176, nb = r % 176;
;                 transpose_item(p.in[I_FFNWIN] + (size_t)mi * D * NFF1, D, NFF1, (bf16_t*)(ws + WS_W1T + mi * SZ_W1T), paired_src(nb * 32, DFF), nb * 32, kb * 64, scr, lane); continue; }
;             r -= 4 * I_W1;
;             if (r < 4 * I_W2) { const int mi = r / I_W2; r -= mi * I_W2; const int kb = r / 32, nb = r % 32;
;                 transpose_item(p.in[I_FFNWOUT] + (size_t)mi * DFF * D, DFF, D, (bf16_t*)(ws + WS_W2T + mi * SZ_W2T), nb * 32, nb * 32, kb * 64, scr, lane); continue; }
.LBB0_1562:
	s_waitcnt vmcnt(0)
	s_barrier
	s_cmpk_lg_u32 s78, 0x100
	s_cbranch_scc1 .Ltr_done_c
	s_cmpk_lt_u32 s68, 0x80
	s_cbranch_scc1 .Ltr_done_c
	s_mov_b64 s[38:39], exec
	s_mov_b64 exec, -1
	v_readfirstlane_b32 s99, v176
	s_lshr_b32 s99, s99, 6
	s_sub_i32 s37, s68, 0x80
	s_lshl_b32 s36, s37, 3
	s_add_i32 s36, s36, s99
	s_lshl_b32 s99, s99, 14
	v_and_b32_e32 v16, 63, v176
	v_and_b32_e32 v17, 31, v16
	v_lshrrev_b32_e32 v18, 5, v16
	v_mul_u32_u24_e32 v19, 0x84, v18
	v_lshl_add_u32 v19, v17, 2, v19
	v_add_u32_e32 v19, s99, v19
	v_and_b32_e32 v20, 7, v16
	v_lshrrev_b32_e32 v21, 3, v16
	v_mul_u32_u24_e32 v22, 0x420, v20
	v_lshl_add_u32 v22, v21, 2, v22
	v_add_u32_e32 v22, s99, v22
	v_lshlrev_b32_e32 v23, 12, v18
	v_lshl_add_u32 v23, v17, 2, v23
	v_mul_u32_u24_e32 v24, 0x1600, v21
	v_lshl_add_u32 v24, v20, 4, v24
	v_readlane_b32 s32, v253, 0
	v_readlane_b32 s33, v253, 1
	s_add_u32 s32, s32, 0x2100000
	s_addc_u32 s33, s33, 0
	s_add_u32 s34, s76, 0x3e80000
	s_addc_u32 s35, s77, 0
	s_mov_b32 s98, s36
	s_cmpk_ge_u32 s98, 0x580
	s_cbranch_scc1 .Ltr_end_c0
